# v7 + remove all remaining s_setprio flips around the MFMA blocks of the GEMM main loops
# speedup vs baseline: 1.0019x; 1.0019x over previous
.LBB0_295:
	ds_read_b128 v[146:149], v155
	ds_read_b128 v[160:163], v155 offset:1024
	ds_read_b128 v[164:167], v155 offset:2048
	ds_read_b128 v[168:171], v155 offset:3072
	ds_read_b128 v[172:175], v156
	ds_read_b128 v[176:179], v156 offset:1024
	ds_read_b128 v[180:183], v156 offset:2048
	ds_read_b128 v[184:187], v156 offset:3072
	s_add_u32 s23, s64, 0xfffc0080
	s_addc_u32 s33, s65, -1
	s_cmp_eq_u32 s92, 12
	s_cselect_b32 s73, s20, s33
	s_cselect_b32 s72, s21, s23
	s_cselect_b32 s71, s19, s91
	s_cselect_b32 s70, s55, s90
	v_lshl_add_u64 v[150:151], s[64:65], 0, v[138:139]
	s_add_i32 m0, s76, 0xc000
	ds_read_b128 v[188:191], v157
	ds_read_b128 v[192:195], v157 offset:1024
	ds_read_b128 v[196:199], v157 offset:2048
	ds_read_b128 v[200:203], v157 offset:3072
	ds_read_b128 v[204:207], v157 offset:4096
	ds_read_b128 v[208:211], v157 offset:5120
	ds_read_b128 v[212:215], v157 offset:6144
	ds_read_b128 v[216:219], v157 offset:7168
	global_load_lds_dwordx4 v[150:151], off
	v_lshl_add_u64 v[150:151], s[64:65], 0, v[140:141]
	s_add_i32 m0, s76, 0xe000
	s_nop 0
	global_load_lds_dwordx4 v[150:151], off
	s_waitcnt vmcnt(8)
	s_waitcnt lgkmcnt(0)
	s_barrier
	v_mfma_f32_16x16x32_bf16 v[124:127], v[146:149], v[188:191], v[124:127]
	v_mfma_f32_16x16x32_bf16 v[120:123], v[164:167], v[188:191], v[120:123]
	v_mfma_f32_16x16x32_bf16 v[108:111], v[146:149], v[196:199], v[108:111]
	v_mfma_f32_16x16x32_bf16 v[104:107], v[164:167], v[196:199], v[104:107]
	v_mfma_f32_16x16x32_bf16 v[92:95], v[146:149], v[204:207], v[92:95]
	v_mfma_f32_16x16x32_bf16 v[88:91], v[164:167], v[204:207], v[88:91]
	v_mfma_f32_16x16x32_bf16 v[76:79], v[146:149], v[212:215], v[76:79]
	v_mfma_f32_16x16x32_bf16 v[72:75], v[164:167], v[212:215], v[72:75]
	v_mfma_f32_16x16x32_bf16 v[124:127], v[160:163], v[192:195], v[124:127]
	v_mfma_f32_16x16x32_bf16 v[120:123], v[168:171], v[192:195], v[120:123]
	v_mfma_f32_16x16x32_bf16 v[108:111], v[160:163], v[200:203], v[108:111]
	v_mfma_f32_16x16x32_bf16 v[104:107], v[168:171], v[200:203], v[104:107]
	v_mfma_f32_16x16x32_bf16 v[92:95], v[160:163], v[208:211], v[92:95]
	v_mfma_f32_16x16x32_bf16 v[88:91], v[168:171], v[208:211], v[88:91]
	v_mfma_f32_16x16x32_bf16 v[76:79], v[160:163], v[216:219], v[76:79]
	v_mfma_f32_16x16x32_bf16 v[72:75], v[168:171], v[216:219], v[72:75]
	v_mfma_f32_16x16x32_bf16 v[116:119], v[172:175], v[188:191], v[116:119]
	v_mfma_f32_16x16x32_bf16 v[112:115], v[180:183], v[188:191], v[112:115]
	v_mfma_f32_16x16x32_bf16 v[100:103], v[172:175], v[196:199], v[100:103]
	v_mfma_f32_16x16x32_bf16 v[96:99], v[180:183], v[196:199], v[96:99]
	v_mfma_f32_16x16x32_bf16 v[84:87], v[172:175], v[204:207], v[84:87]
	v_mfma_f32_16x16x32_bf16 v[80:83], v[180:183], v[204:207], v[80:83]
	v_mfma_f32_16x16x32_bf16 v[68:71], v[172:175], v[212:215], v[68:71]
	v_mfma_f32_16x16x32_bf16 v[64:67], v[180:183], v[212:215], v[64:67]
	v_mfma_f32_16x16x32_bf16 v[116:119], v[176:179], v[192:195], v[116:119]
	v_mfma_f32_16x16x32_bf16 v[112:115], v[184:187], v[192:195], v[112:115]
	v_mfma_f32_16x16x32_bf16 v[100:103], v[176:179], v[200:203], v[100:103]
	v_mfma_f32_16x16x32_bf16 v[96:99], v[184:187], v[200:203], v[96:99]
	v_mfma_f32_16x16x32_bf16 v[84:87], v[176:179], v[208:211], v[84:87]
	v_mfma_f32_16x16x32_bf16 v[80:83], v[184:187], v[208:211], v[80:83]
	v_mfma_f32_16x16x32_bf16 v[68:71], v[176:179], v[216:219], v[68:71]
	v_mfma_f32_16x16x32_bf16 v[64:67], v[184:187], v[216:219], v[64:67]
	s_barrier
	s_add_i32 s23, s85, s74
	v_lshl_add_u64 v[150:151], s[70:71], 0, v[132:133]
	s_mov_b32 m0, s23
	ds_read_b128 v[188:191], v157 offset:16384
	ds_read_b128 v[192:195], v157 offset:17408
	ds_read_b128 v[196:199], v157 offset:18432
	ds_read_b128 v[200:203], v157 offset:19456
	ds_read_b128 v[204:207], v157 offset:20480
	ds_read_b128 v[208:211], v157 offset:21504
	ds_read_b128 v[212:215], v157 offset:22528
	ds_read_b128 v[216:219], v157 offset:23552
	global_load_lds_dwordx4 v[150:151], off
	s_add_i32 m0, s23, 0x2000
	s_add_u32 s94, s70, 0x40000
	v_lshl_add_u64 v[220:221], s[70:71], 0, v[136:137]
	s_addc_u32 s95, s71, 0
	s_add_i32 s23, s86, s74
	global_load_lds_dwordx4 v[220:221], off
	v_lshl_add_u64 v[222:223], s[94:95], 0, v[132:133]
	s_mov_b32 m0, s23
	v_lshl_add_u64 v[224:225], s[72:73], 0, v[134:135]
	global_load_lds_dwordx4 v[222:223], off
	v_lshl_add_u64 v[222:223], s[94:95], 0, v[136:137]
	s_add_i32 m0, s23, 0x2000
	s_nop 0
	global_load_lds_dwordx4 v[222:223], off
	v_lshl_add_u64 v[222:223], s[72:73], 0, v[130:131]
	s_mov_b32 m0, s76
	s_nop 0
	global_load_lds_dwordx4 v[222:223], off
	s_mov_b32 m0, s77
	s_nop 0
	global_load_lds_dwordx4 v[224:225], off
	s_waitcnt vmcnt(8)
	s_waitcnt lgkmcnt(0)
	s_barrier
	v_mfma_f32_16x16x32_bf16 v[60:63], v[146:149], v[188:191], v[60:63]
	v_mfma_f32_16x16x32_bf16 v[56:59], v[164:167], v[188:191], v[56:59]
	v_mfma_f32_16x16x32_bf16 v[44:47], v[146:149], v[196:199], v[44:47]
	v_mfma_f32_16x16x32_bf16 v[40:43], v[164:167], v[196:199], v[40:43]
	v_mfma_f32_16x16x32_bf16 v[28:31], v[146:149], v[204:207], v[28:31]
	v_mfma_f32_16x16x32_bf16 v[24:27], v[164:167], v[204:207], v[24:27]
	v_mfma_f32_16x16x32_bf16 v[12:15], v[146:149], v[212:215], v[12:15]
	v_mfma_f32_16x16x32_bf16 v[8:11], v[164:167], v[212:215], v[8:11]
	v_mfma_f32_16x16x32_bf16 v[60:63], v[160:163], v[192:195], v[60:63]
	v_mfma_f32_16x16x32_bf16 v[56:59], v[168:171], v[192:195], v[56:59]
	v_mfma_f32_16x16x32_bf16 v[44:47], v[160:163], v[200:203], v[44:47]
	v_mfma_f32_16x16x32_bf16 v[40:43], v[168:171], v[200:203], v[40:43]
	v_mfma_f32_16x16x32_bf16 v[28:31], v[160:163], v[208:211], v[28:31]
	v_mfma_f32_16x16x32_bf16 v[24:27], v[168:171], v[208:211], v[24:27]
	v_mfma_f32_16x16x32_bf16 v[12:15], v[160:163], v[216:219], v[12:15]
	v_mfma_f32_16x16x32_bf16 v[8:11], v[168:171], v[216:219], v[8:11]
	v_mfma_f32_16x16x32_bf16 v[52:55], v[172:175], v[188:191], v[52:55]
	v_mfma_f32_16x16x32_bf16 v[48:51], v[180:183], v[188:191], v[48:51]
	v_mfma_f32_16x16x32_bf16 v[36:39], v[172:175], v[196:199], v[36:39]
	v_mfma_f32_16x16x32_bf16 v[32:35], v[180:183], v[196:199], v[32:35]
	v_mfma_f32_16x16x32_bf16 v[20:23], v[172:175], v[204:207], v[20:23]
	v_mfma_f32_16x16x32_bf16 v[16:19], v[180:183], v[204:207], v[16:19]
	v_mfma_f32_16x16x32_bf16 v[4:7], v[172:175], v[212:215], v[4:7]
	v_mfma_f32_16x16x32_bf16 v[0:3], v[180:183], v[212:215], v[0:3]
	v_mfma_f32_16x16x32_bf16 v[52:55], v[176:179], v[192:195], v[52:55]
	v_mfma_f32_16x16x32_bf16 v[48:51], v[184:187], v[192:195], v[48:51]
	v_mfma_f32_16x16x32_bf16 v[36:39], v[176:179], v[200:203], v[36:39]
	v_mfma_f32_16x16x32_bf16 v[32:35], v[184:187], v[200:203], v[32:35]
	v_mfma_f32_16x16x32_bf16 v[20:23], v[176:179], v[208:211], v[20:23]
	v_mfma_f32_16x16x32_bf16 v[16:19], v[184:187], v[208:211], v[16:19]
	v_mfma_f32_16x16x32_bf16 v[4:7], v[176:179], v[216:219], v[4:7]
	v_mfma_f32_16x16x32_bf16 v[0:3], v[184:187], v[216:219], v[0:3]
	s_barrier
	s_add_i32 s23, 0, 0x18000
	v_add_u32_e32 v159, s23, v153
	s_add_i32 s33, 0, 0x1c000
	ds_read_b128 v[146:149], v159
	ds_read_b128 v[160:163], v159 offset:1024
	ds_read_b128 v[164:167], v159 offset:2048
	ds_read_b128 v[168:171], v159 offset:3072
	v_add_u32_e32 v159, s33, v153
	ds_read_b128 v[172:175], v159
	ds_read_b128 v[176:179], v159 offset:1024
	ds_read_b128 v[180:183], v159 offset:2048
	ds_read_b128 v[184:187], v159 offset:3072
	s_add_u32 s72, s72, 0x40000
	s_addc_u32 s73, s73, 0
	s_mov_b32 m0, s78
	v_lshl_add_u64 v[226:227], s[72:73], 0, v[130:131]
	ds_read_b128 v[188:191], v157 offset:32768
	ds_read_b128 v[192:195], v157 offset:33792
	ds_read_b128 v[196:199], v157 offset:34816
	ds_read_b128 v[200:203], v157 offset:35840
	ds_read_b128 v[204:207], v157 offset:36864
	ds_read_b128 v[208:211], v157 offset:37888
	ds_read_b128 v[212:215], v157 offset:38912
	ds_read_b128 v[216:219], v157 offset:39936
	global_load_lds_dwordx4 v[226:227], off
	v_lshl_add_u64 v[226:227], s[72:73], 0, v[134:135]
	s_mov_b32 m0, s79
	s_nop 0
	global_load_lds_dwordx4 v[226:227], off
	s_waitcnt vmcnt(8)
	s_waitcnt lgkmcnt(0)
	s_barrier
	v_mfma_f32_16x16x32_bf16 v[124:127], v[146:149], v[188:191], v[124:127]
	v_mfma_f32_16x16x32_bf16 v[120:123], v[164:167], v[188:191], v[120:123]
	v_mfma_f32_16x16x32_bf16 v[108:111], v[146:149], v[196:199], v[108:111]
	v_mfma_f32_16x16x32_bf16 v[104:107], v[164:167], v[196:199], v[104:107]
	v_mfma_f32_16x16x32_bf16 v[92:95], v[146:149], v[204:207], v[92:95]
	v_mfma_f32_16x16x32_bf16 v[88:91], v[164:167], v[204:207], v[88:91]
	v_mfma_f32_16x16x32_bf16 v[76:79], v[146:149], v[212:215], v[76:79]
	v_mfma_f32_16x16x32_bf16 v[72:75], v[164:167], v[212:215], v[72:75]
	v_mfma_f32_16x16x32_bf16 v[124:127], v[160:163], v[192:195], v[124:127]
	v_mfma_f32_16x16x32_bf16 v[120:123], v[168:171], v[192:195], v[120:123]
	v_mfma_f32_16x16x32_bf16 v[108:111], v[160:163], v[200:203], v[108:111]
	v_mfma_f32_16x16x32_bf16 v[104:107], v[168:171], v[200:203], v[104:107]
	v_mfma_f32_16x16x32_bf16 v[92:95], v[160:163], v[208:211], v[92:95]
	v_mfma_f32_16x16x32_bf16 v[88:91], v[168:171], v[208:211], v[88:91]
	v_mfma_f32_16x16x32_bf16 v[76:79], v[160:163], v[216:219], v[76:79]
	v_mfma_f32_16x16x32_bf16 v[72:75], v[168:171], v[216:219], v[72:75]
	v_mfma_f32_16x16x32_bf16 v[116:119], v[172:175], v[188:191], v[116:119]
	v_mfma_f32_16x16x32_bf16 v[112:115], v[180:183], v[188:191], v[112:115]
	v_mfma_f32_16x16x32_bf16 v[100:103], v[172:175], v[196:199], v[100:103]
	v_mfma_f32_16x16x32_bf16 v[96:99], v[180:183], v[196:199], v[96:99]
	v_mfma_f32_16x16x32_bf16 v[84:87], v[172:175], v[204:207], v[84:87]
	v_mfma_f32_16x16x32_bf16 v[80:83], v[180:183], v[204:207], v[80:83]
	v_mfma_f32_16x16x32_bf16 v[68:71], v[172:175], v[212:215], v[68:71]
	v_mfma_f32_16x16x32_bf16 v[64:67], v[180:183], v[212:215], v[64:67]
	v_mfma_f32_16x16x32_bf16 v[116:119], v[176:179], v[192:195], v[116:119]
	v_mfma_f32_16x16x32_bf16 v[112:115], v[184:187], v[192:195], v[112:115]
	v_mfma_f32_16x16x32_bf16 v[100:103], v[176:179], v[200:203], v[100:103]
	v_mfma_f32_16x16x32_bf16 v[96:99], v[184:187], v[200:203], v[96:99]
	v_mfma_f32_16x16x32_bf16 v[84:87], v[176:179], v[208:211], v[84:87]
	v_mfma_f32_16x16x32_bf16 v[80:83], v[184:187], v[208:211], v[80:83]
	v_mfma_f32_16x16x32_bf16 v[68:71], v[176:179], v[216:219], v[68:71]
	v_mfma_f32_16x16x32_bf16 v[64:67], v[184:187], v[216:219], v[64:67]
	s_barrier
	s_add_i32 s23, s23, s74
	v_lshl_add_u64 v[150:151], v[150:151], 0, s[10:11]
	s_mov_b32 m0, s23
	ds_read_b128 v[188:191], v157 offset:49152
	ds_read_b128 v[192:195], v157 offset:50176
	ds_read_b128 v[196:199], v157 offset:51200
	ds_read_b128 v[200:203], v157 offset:52224
	ds_read_b128 v[204:207], v157 offset:53248
	ds_read_b128 v[208:211], v157 offset:54272
	ds_read_b128 v[212:215], v157 offset:55296
	ds_read_b128 v[216:219], v157 offset:56320
	global_load_lds_dwordx4 v[150:151], off
	s_add_i32 m0, s23, 0x2000
	s_add_u32 s70, s70, 0x40080
	v_lshl_add_u64 v[150:151], v[220:221], 0, s[10:11]
	s_addc_u32 s71, s71, 0
	s_add_i32 s23, s33, s74
	global_load_lds_dwordx4 v[150:151], off
	v_lshl_add_u64 v[150:151], s[70:71], 0, v[132:133]
	s_mov_b32 m0, s23
	s_nop 0
	global_load_lds_dwordx4 v[150:151], off
	v_lshl_add_u64 v[150:151], s[70:71], 0, v[136:137]
	s_add_i32 m0, s23, 0x2000
	s_nop 0
	global_load_lds_dwordx4 v[150:151], off
	v_lshl_add_u64 v[150:151], v[222:223], 0, s[10:11]
	s_mov_b32 m0, s82
	s_nop 0
	global_load_lds_dwordx4 v[150:151], off
	v_lshl_add_u64 v[150:151], v[224:225], 0, s[10:11]
	s_mov_b32 m0, s83
	s_nop 0
	global_load_lds_dwordx4 v[150:151], off
	s_waitcnt vmcnt(8)
	s_waitcnt lgkmcnt(0)
	s_barrier
	v_mfma_f32_16x16x32_bf16 v[60:63], v[146:149], v[188:191], v[60:63]
	v_mfma_f32_16x16x32_bf16 v[56:59], v[164:167], v[188:191], v[56:59]
	v_mfma_f32_16x16x32_bf16 v[44:47], v[146:149], v[196:199], v[44:47]
	v_mfma_f32_16x16x32_bf16 v[40:43], v[164:167], v[196:199], v[40:43]
	v_mfma_f32_16x16x32_bf16 v[28:31], v[146:149], v[204:207], v[28:31]
	v_mfma_f32_16x16x32_bf16 v[24:27], v[164:167], v[204:207], v[24:27]
	v_mfma_f32_16x16x32_bf16 v[12:15], v[146:149], v[212:215], v[12:15]
	v_mfma_f32_16x16x32_bf16 v[8:11], v[164:167], v[212:215], v[8:11]
	v_mfma_f32_16x16x32_bf16 v[60:63], v[160:163], v[192:195], v[60:63]
	v_mfma_f32_16x16x32_bf16 v[56:59], v[168:171], v[192:195], v[56:59]
	v_mfma_f32_16x16x32_bf16 v[44:47], v[160:163], v[200:203], v[44:47]
	v_mfma_f32_16x16x32_bf16 v[40:43], v[168:171], v[200:203], v[40:43]
	v_mfma_f32_16x16x32_bf16 v[28:31], v[160:163], v[208:211], v[28:31]
	v_mfma_f32_16x16x32_bf16 v[24:27], v[168:171], v[208:211], v[24:27]
	v_mfma_f32_16x16x32_bf16 v[12:15], v[160:163], v[216:219], v[12:15]
	v_mfma_f32_16x16x32_bf16 v[8:11], v[168:171], v[216:219], v[8:11]
	v_mfma_f32_16x16x32_bf16 v[52:55], v[172:175], v[188:191], v[52:55]
	v_mfma_f32_16x16x32_bf16 v[48:51], v[180:183], v[188:191], v[48:51]
	v_mfma_f32_16x16x32_bf16 v[36:39], v[172:175], v[196:199], v[36:39]
	v_mfma_f32_16x16x32_bf16 v[32:35], v[180:183], v[196:199], v[32:35]
	v_mfma_f32_16x16x32_bf16 v[20:23], v[172:175], v[204:207], v[20:23]
	v_mfma_f32_16x16x32_bf16 v[16:19], v[180:183], v[204:207], v[16:19]
	v_mfma_f32_16x16x32_bf16 v[4:7], v[172:175], v[212:215], v[4:7]
	v_mfma_f32_16x16x32_bf16 v[0:3], v[180:183], v[212:215], v[0:3]
	v_mfma_f32_16x16x32_bf16 v[52:55], v[176:179], v[192:195], v[52:55]
	v_mfma_f32_16x16x32_bf16 v[48:51], v[184:187], v[192:195], v[48:51]
	v_mfma_f32_16x16x32_bf16 v[36:39], v[176:179], v[200:203], v[36:39]
	v_mfma_f32_16x16x32_bf16 v[32:35], v[184:187], v[200:203], v[32:35]
	v_mfma_f32_16x16x32_bf16 v[20:23], v[176:179], v[208:211], v[20:23]
	v_mfma_f32_16x16x32_bf16 v[16:19], v[184:187], v[208:211], v[16:19]
	v_mfma_f32_16x16x32_bf16 v[4:7], v[176:179], v[216:219], v[4:7]
	v_mfma_f32_16x16x32_bf16 v[0:3], v[184:187], v[216:219], v[0:3]
	s_barrier
	s_add_i32 s92, s92, 2
	s_add_u32 s64, s64, 0x100
	s_addc_u32 s65, s65, 0
	s_add_u32 s90, s90, 0x100
	s_addc_u32 s91, s91, 0
	s_cmp_gt_u32 s92, 13
	s_cbranch_scc0 .LBB0_295
	s_and_b64 vcc, exec, s[14:15]
	s_cbranch_vccz .LBB0_298
	s_barrier

.LBB0_437:
	ds_read_b128 v[146:149], v139
	ds_read_b128 v[150:153], v139 offset:1024
	ds_read_b128 v[154:157], v139 offset:2048
	ds_read_b128 v[158:161], v139 offset:3072
	ds_read_b128 v[162:165], v141
	ds_read_b128 v[166:169], v141 offset:1024
	ds_read_b128 v[170:173], v141 offset:2048
	ds_read_b128 v[174:177], v141 offset:3072
	s_add_u32 s10, s6, s8
	s_addc_u32 s11, s7, s9
	s_add_u32 s10, s10, 0x2300100
	s_addc_u32 s11, s11, 0
	s_add_u32 s23, s69, s8
	s_addc_u32 s33, s70, s9
	s_cmpk_eq_i32 s8, 0x700
	s_cselect_b32 s13, s3, s11
	s_cselect_b32 s12, s2, s10
	s_cselect_b32 s11, s1, s33
	s_cselect_b32 s10, s0, s23
	s_mov_b32 m0, s72
	v_lshl_add_u64 v[210:211], v[134:135], 0, s[8:9]
	ds_read_b128 v[178:181], v142
	ds_read_b128 v[182:185], v142 offset:1024
	ds_read_b128 v[186:189], v142 offset:2048
	ds_read_b128 v[190:193], v142 offset:3072
	ds_read_b128 v[194:197], v142 offset:4096
	ds_read_b128 v[198:201], v142 offset:5120
	ds_read_b128 v[202:205], v142 offset:6144
	ds_read_b128 v[206:209], v142 offset:7168
	global_load_lds_dwordx4 v[210:211], off
	v_lshl_add_u64 v[210:211], v[136:137], 0, s[8:9]
	s_mov_b32 m0, s73
	s_nop 0
	global_load_lds_dwordx4 v[210:211], off
	s_waitcnt vmcnt(8)
	s_waitcnt lgkmcnt(0)
	s_barrier
	v_mfma_f32_16x16x32_bf16 v[124:127], v[146:149], v[178:181], v[124:127]
	v_mfma_f32_16x16x32_bf16 v[120:123], v[154:157], v[178:181], v[120:123]
	v_mfma_f32_16x16x32_bf16 v[108:111], v[146:149], v[186:189], v[108:111]
	v_mfma_f32_16x16x32_bf16 v[104:107], v[154:157], v[186:189], v[104:107]
	v_mfma_f32_16x16x32_bf16 v[92:95], v[146:149], v[194:197], v[92:95]
	v_mfma_f32_16x16x32_bf16 v[88:91], v[154:157], v[194:197], v[88:91]
	v_mfma_f32_16x16x32_bf16 v[76:79], v[146:149], v[202:205], v[76:79]
	v_mfma_f32_16x16x32_bf16 v[72:75], v[154:157], v[202:205], v[72:75]
	v_mfma_f32_16x16x32_bf16 v[124:127], v[150:153], v[182:185], v[124:127]
	v_mfma_f32_16x16x32_bf16 v[120:123], v[158:161], v[182:185], v[120:123]
	v_mfma_f32_16x16x32_bf16 v[108:111], v[150:153], v[190:193], v[108:111]
	v_mfma_f32_16x16x32_bf16 v[104:107], v[158:161], v[190:193], v[104:107]
	v_mfma_f32_16x16x32_bf16 v[92:95], v[150:153], v[198:201], v[92:95]
	v_mfma_f32_16x16x32_bf16 v[88:91], v[158:161], v[198:201], v[88:91]
	v_mfma_f32_16x16x32_bf16 v[76:79], v[150:153], v[206:209], v[76:79]
	v_mfma_f32_16x16x32_bf16 v[72:75], v[158:161], v[206:209], v[72:75]
	v_mfma_f32_16x16x32_bf16 v[116:119], v[162:165], v[178:181], v[116:119]
	v_mfma_f32_16x16x32_bf16 v[112:115], v[170:173], v[178:181], v[112:115]
	v_mfma_f32_16x16x32_bf16 v[100:103], v[162:165], v[186:189], v[100:103]
	v_mfma_f32_16x16x32_bf16 v[96:99], v[170:173], v[186:189], v[96:99]
	v_mfma_f32_16x16x32_bf16 v[84:87], v[162:165], v[194:197], v[84:87]
	v_mfma_f32_16x16x32_bf16 v[80:83], v[170:173], v[194:197], v[80:83]
	v_mfma_f32_16x16x32_bf16 v[68:71], v[162:165], v[202:205], v[68:71]
	v_mfma_f32_16x16x32_bf16 v[64:67], v[170:173], v[202:205], v[64:67]
	v_mfma_f32_16x16x32_bf16 v[116:119], v[166:169], v[182:185], v[116:119]
	v_mfma_f32_16x16x32_bf16 v[112:115], v[174:177], v[182:185], v[112:115]
	v_mfma_f32_16x16x32_bf16 v[100:103], v[166:169], v[190:193], v[100:103]
	v_mfma_f32_16x16x32_bf16 v[96:99], v[174:177], v[190:193], v[96:99]
	v_mfma_f32_16x16x32_bf16 v[84:87], v[166:169], v[198:201], v[84:87]
	v_mfma_f32_16x16x32_bf16 v[80:83], v[174:177], v[198:201], v[80:83]
	v_mfma_f32_16x16x32_bf16 v[68:71], v[166:169], v[206:209], v[68:71]
	v_mfma_f32_16x16x32_bf16 v[64:67], v[174:177], v[206:209], v[64:67]
	s_barrier
	s_mov_b32 m0, s74
	v_lshl_add_u64 v[210:211], s[10:11], 0, v[132:133]
	s_add_u32 s82, s10, 0x40000
	ds_read_b128 v[178:181], v142 offset:16384
	ds_read_b128 v[182:185], v142 offset:17408
	ds_read_b128 v[186:189], v142 offset:18432
	ds_read_b128 v[190:193], v142 offset:19456
	ds_read_b128 v[194:197], v142 offset:20480
	ds_read_b128 v[198:201], v142 offset:21504
	ds_read_b128 v[202:205], v142 offset:22528
	ds_read_b128 v[206:209], v142 offset:23552
	global_load_lds_dwordx4 v[210:211], off
	v_lshl_add_u64 v[212:213], s[10:11], 0, v[130:131]
	s_mov_b32 m0, s75
	s_addc_u32 s83, s11, 0
	global_load_lds_dwordx4 v[212:213], off
	v_lshl_add_u64 v[214:215], s[82:83], 0, v[132:133]
	s_mov_b32 m0, s76
	v_lshl_add_u64 v[216:217], s[12:13], 0, v[130:131]
	global_load_lds_dwordx4 v[214:215], off
	v_lshl_add_u64 v[214:215], s[82:83], 0, v[130:131]
	s_mov_b32 m0, s77
	s_nop 0
	global_load_lds_dwordx4 v[214:215], off
	v_lshl_add_u64 v[214:215], s[12:13], 0, v[132:133]
	s_mov_b32 m0, s17
	s_nop 0
	global_load_lds_dwordx4 v[214:215], off
	s_mov_b32 m0, s20
	s_nop 0
	global_load_lds_dwordx4 v[216:217], off
	s_waitcnt vmcnt(8)
	s_waitcnt lgkmcnt(0)
	s_barrier
	v_mfma_f32_16x16x32_bf16 v[60:63], v[146:149], v[178:181], v[60:63]
	v_mfma_f32_16x16x32_bf16 v[56:59], v[154:157], v[178:181], v[56:59]
	v_mfma_f32_16x16x32_bf16 v[44:47], v[146:149], v[186:189], v[44:47]
	v_mfma_f32_16x16x32_bf16 v[40:43], v[154:157], v[186:189], v[40:43]
	v_mfma_f32_16x16x32_bf16 v[28:31], v[146:149], v[194:197], v[28:31]
	v_mfma_f32_16x16x32_bf16 v[24:27], v[154:157], v[194:197], v[24:27]
	v_mfma_f32_16x16x32_bf16 v[12:15], v[146:149], v[202:205], v[12:15]
	v_mfma_f32_16x16x32_bf16 v[8:11], v[154:157], v[202:205], v[8:11]
	v_mfma_f32_16x16x32_bf16 v[60:63], v[150:153], v[182:185], v[60:63]
	v_mfma_f32_16x16x32_bf16 v[56:59], v[158:161], v[182:185], v[56:59]
	v_mfma_f32_16x16x32_bf16 v[44:47], v[150:153], v[190:193], v[44:47]
	v_mfma_f32_16x16x32_bf16 v[40:43], v[158:161], v[190:193], v[40:43]
	v_mfma_f32_16x16x32_bf16 v[28:31], v[150:153], v[198:201], v[28:31]
	v_mfma_f32_16x16x32_bf16 v[24:27], v[158:161], v[198:201], v[24:27]
	v_mfma_f32_16x16x32_bf16 v[12:15], v[150:153], v[206:209], v[12:15]
	v_mfma_f32_16x16x32_bf16 v[8:11], v[158:161], v[206:209], v[8:11]
	v_mfma_f32_16x16x32_bf16 v[52:55], v[162:165], v[178:181], v[52:55]
	v_mfma_f32_16x16x32_bf16 v[48:51], v[170:173], v[178:181], v[48:51]
	v_mfma_f32_16x16x32_bf16 v[36:39], v[162:165], v[186:189], v[36:39]
	v_mfma_f32_16x16x32_bf16 v[32:35], v[170:173], v[186:189], v[32:35]
	v_mfma_f32_16x16x32_bf16 v[20:23], v[162:165], v[194:197], v[20:23]
	v_mfma_f32_16x16x32_bf16 v[16:19], v[170:173], v[194:197], v[16:19]
	v_mfma_f32_16x16x32_bf16 v[4:7], v[162:165], v[202:205], v[4:7]
	v_mfma_f32_16x16x32_bf16 v[0:3], v[170:173], v[202:205], v[0:3]
	v_mfma_f32_16x16x32_bf16 v[52:55], v[166:169], v[182:185], v[52:55]
	v_mfma_f32_16x16x32_bf16 v[48:51], v[174:177], v[182:185], v[48:51]
	v_mfma_f32_16x16x32_bf16 v[36:39], v[166:169], v[190:193], v[36:39]
	v_mfma_f32_16x16x32_bf16 v[32:35], v[174:177], v[190:193], v[32:35]
	v_mfma_f32_16x16x32_bf16 v[20:23], v[166:169], v[198:201], v[20:23]
	v_mfma_f32_16x16x32_bf16 v[16:19], v[174:177], v[198:201], v[16:19]
	v_mfma_f32_16x16x32_bf16 v[4:7], v[166:169], v[206:209], v[4:7]
	v_mfma_f32_16x16x32_bf16 v[0:3], v[174:177], v[206:209], v[0:3]
	s_barrier
	ds_read_b128 v[146:149], v143
	ds_read_b128 v[150:153], v143 offset:1024
	ds_read_b128 v[154:157], v143 offset:2048
	ds_read_b128 v[158:161], v143 offset:3072
	ds_read_b128 v[162:165], v144
	ds_read_b128 v[166:169], v144 offset:1024
	ds_read_b128 v[170:173], v144 offset:2048
	ds_read_b128 v[174:177], v144 offset:3072
	s_add_u32 s12, s12, 0x40000
	s_addc_u32 s13, s13, 0
	s_mov_b32 m0, s21
	v_lshl_add_u64 v[218:219], s[12:13], 0, v[132:133]
	ds_read_b128 v[178:181], v142 offset:32768
	ds_read_b128 v[182:185], v142 offset:33792
	ds_read_b128 v[186:189], v142 offset:34816
	ds_read_b128 v[190:193], v142 offset:35840
	ds_read_b128 v[194:197], v142 offset:36864
	ds_read_b128 v[198:201], v142 offset:37888
	ds_read_b128 v[202:205], v142 offset:38912
	ds_read_b128 v[206:209], v142 offset:39936
	global_load_lds_dwordx4 v[218:219], off
	v_lshl_add_u64 v[218:219], s[12:13], 0, v[130:131]
	s_mov_b32 m0, s58
	s_nop 0
	global_load_lds_dwordx4 v[218:219], off
	s_waitcnt vmcnt(8)
	s_waitcnt lgkmcnt(0)
	s_barrier
	v_mfma_f32_16x16x32_bf16 v[124:127], v[146:149], v[178:181], v[124:127]
	v_mfma_f32_16x16x32_bf16 v[120:123], v[154:157], v[178:181], v[120:123]
	v_mfma_f32_16x16x32_bf16 v[108:111], v[146:149], v[186:189], v[108:111]
	v_mfma_f32_16x16x32_bf16 v[104:107], v[154:157], v[186:189], v[104:107]
	v_mfma_f32_16x16x32_bf16 v[92:95], v[146:149], v[194:197], v[92:95]
	v_mfma_f32_16x16x32_bf16 v[88:91], v[154:157], v[194:197], v[88:91]
	v_mfma_f32_16x16x32_bf16 v[76:79], v[146:149], v[202:205], v[76:79]
	v_mfma_f32_16x16x32_bf16 v[72:75], v[154:157], v[202:205], v[72:75]
	v_mfma_f32_16x16x32_bf16 v[124:127], v[150:153], v[182:185], v[124:127]
	v_mfma_f32_16x16x32_bf16 v[120:123], v[158:161], v[182:185], v[120:123]
	v_mfma_f32_16x16x32_bf16 v[108:111], v[150:153], v[190:193], v[108:111]
	v_mfma_f32_16x16x32_bf16 v[104:107], v[158:161], v[190:193], v[104:107]
	v_mfma_f32_16x16x32_bf16 v[92:95], v[150:153], v[198:201], v[92:95]
	v_mfma_f32_16x16x32_bf16 v[88:91], v[158:161], v[198:201], v[88:91]
	v_mfma_f32_16x16x32_bf16 v[76:79], v[150:153], v[206:209], v[76:79]
	v_mfma_f32_16x16x32_bf16 v[72:75], v[158:161], v[206:209], v[72:75]
	v_mfma_f32_16x16x32_bf16 v[116:119], v[162:165], v[178:181], v[116:119]
	v_mfma_f32_16x16x32_bf16 v[112:115], v[170:173], v[178:181], v[112:115]
	v_mfma_f32_16x16x32_bf16 v[100:103], v[162:165], v[186:189], v[100:103]
	v_mfma_f32_16x16x32_bf16 v[96:99], v[170:173], v[186:189], v[96:99]
	v_mfma_f32_16x16x32_bf16 v[84:87], v[162:165], v[194:197], v[84:87]
	v_mfma_f32_16x16x32_bf16 v[80:83], v[170:173], v[194:197], v[80:83]
	v_mfma_f32_16x16x32_bf16 v[68:71], v[162:165], v[202:205], v[68:71]
	v_mfma_f32_16x16x32_bf16 v[64:67], v[170:173], v[202:205], v[64:67]
	v_mfma_f32_16x16x32_bf16 v[116:119], v[166:169], v[182:185], v[116:119]
	v_mfma_f32_16x16x32_bf16 v[112:115], v[174:177], v[182:185], v[112:115]
	v_mfma_f32_16x16x32_bf16 v[100:103], v[166:169], v[190:193], v[100:103]
	v_mfma_f32_16x16x32_bf16 v[96:99], v[174:177], v[190:193], v[96:99]
	v_mfma_f32_16x16x32_bf16 v[84:87], v[166:169], v[198:201], v[84:87]
	v_mfma_f32_16x16x32_bf16 v[80:83], v[174:177], v[198:201], v[80:83]
	v_mfma_f32_16x16x32_bf16 v[68:71], v[166:169], v[206:209], v[68:71]
	v_mfma_f32_16x16x32_bf16 v[64:67], v[174:177], v[206:209], v[64:67]
	s_barrier
	s_mov_b32 m0, s78
	v_lshl_add_u64 v[210:211], v[210:211], 0, s[4:5]
	s_add_u32 s10, s10, 0x40080
	ds_read_b128 v[178:181], v142 offset:49152
	ds_read_b128 v[182:185], v142 offset:50176
	ds_read_b128 v[186:189], v142 offset:51200
	ds_read_b128 v[190:193], v142 offset:52224
	ds_read_b128 v[194:197], v142 offset:53248
	ds_read_b128 v[198:201], v142 offset:54272
	ds_read_b128 v[202:205], v142 offset:55296
	ds_read_b128 v[206:209], v142 offset:56320
	global_load_lds_dwordx4 v[210:211], off
	v_lshl_add_u64 v[210:211], v[212:213], 0, s[4:5]
	s_mov_b32 m0, s79
	s_addc_u32 s11, s11, 0
	global_load_lds_dwordx4 v[210:211], off
	v_lshl_add_u64 v[210:211], s[10:11], 0, v[132:133]
	s_mov_b32 m0, s80
	s_nop 0
	global_load_lds_dwordx4 v[210:211], off
	v_lshl_add_u64 v[210:211], s[10:11], 0, v[130:131]
	s_mov_b32 m0, s81
	s_nop 0
	global_load_lds_dwordx4 v[210:211], off
	v_lshl_add_u64 v[210:211], v[214:215], 0, s[4:5]
	s_mov_b32 m0, s65
	s_nop 0
	global_load_lds_dwordx4 v[210:211], off
	v_lshl_add_u64 v[210:211], v[216:217], 0, s[4:5]
	s_mov_b32 m0, s68
	s_nop 0
	global_load_lds_dwordx4 v[210:211], off
	s_waitcnt vmcnt(8)
	s_waitcnt lgkmcnt(0)
	s_barrier
	v_mfma_f32_16x16x32_bf16 v[60:63], v[146:149], v[178:181], v[60:63]
	v_mfma_f32_16x16x32_bf16 v[56:59], v[154:157], v[178:181], v[56:59]
	v_mfma_f32_16x16x32_bf16 v[44:47], v[146:149], v[186:189], v[44:47]
	v_mfma_f32_16x16x32_bf16 v[40:43], v[154:157], v[186:189], v[40:43]
	v_mfma_f32_16x16x32_bf16 v[28:31], v[146:149], v[194:197], v[28:31]
	v_mfma_f32_16x16x32_bf16 v[24:27], v[154:157], v[194:197], v[24:27]
	v_mfma_f32_16x16x32_bf16 v[12:15], v[146:149], v[202:205], v[12:15]
	v_mfma_f32_16x16x32_bf16 v[8:11], v[154:157], v[202:205], v[8:11]
	v_mfma_f32_16x16x32_bf16 v[60:63], v[150:153], v[182:185], v[60:63]
	v_mfma_f32_16x16x32_bf16 v[56:59], v[158:161], v[182:185], v[56:59]
	v_mfma_f32_16x16x32_bf16 v[44:47], v[150:153], v[190:193], v[44:47]
	v_mfma_f32_16x16x32_bf16 v[40:43], v[158:161], v[190:193], v[40:43]
	v_mfma_f32_16x16x32_bf16 v[28:31], v[150:153], v[198:201], v[28:31]
	v_mfma_f32_16x16x32_bf16 v[24:27], v[158:161], v[198:201], v[24:27]
	v_mfma_f32_16x16x32_bf16 v[12:15], v[150:153], v[206:209], v[12:15]
	v_mfma_f32_16x16x32_bf16 v[8:11], v[158:161], v[206:209], v[8:11]
	v_mfma_f32_16x16x32_bf16 v[52:55], v[162:165], v[178:181], v[52:55]
	v_mfma_f32_16x16x32_bf16 v[48:51], v[170:173], v[178:181], v[48:51]
	v_mfma_f32_16x16x32_bf16 v[36:39], v[162:165], v[186:189], v[36:39]
	v_mfma_f32_16x16x32_bf16 v[32:35], v[170:173], v[186:189], v[32:35]
	v_mfma_f32_16x16x32_bf16 v[20:23], v[162:165], v[194:197], v[20:23]
	v_mfma_f32_16x16x32_bf16 v[16:19], v[170:173], v[194:197], v[16:19]
	v_mfma_f32_16x16x32_bf16 v[4:7], v[162:165], v[202:205], v[4:7]
	v_mfma_f32_16x16x32_bf16 v[0:3], v[170:173], v[202:205], v[0:3]
	v_mfma_f32_16x16x32_bf16 v[52:55], v[166:169], v[182:185], v[52:55]
	v_mfma_f32_16x16x32_bf16 v[48:51], v[174:177], v[182:185], v[48:51]
	v_mfma_f32_16x16x32_bf16 v[36:39], v[166:169], v[190:193], v[36:39]
	v_mfma_f32_16x16x32_bf16 v[32:35], v[174:177], v[190:193], v[32:35]
	v_mfma_f32_16x16x32_bf16 v[20:23], v[166:169], v[198:201], v[20:23]
	v_mfma_f32_16x16x32_bf16 v[16:19], v[174:177], v[198:201], v[16:19]
	v_mfma_f32_16x16x32_bf16 v[4:7], v[166:169], v[206:209], v[4:7]
	v_mfma_f32_16x16x32_bf16 v[0:3], v[174:177], v[206:209], v[0:3]
	s_barrier
	s_add_i32 s71, s71, 2
	s_add_u32 s8, s8, 0x100
	s_addc_u32 s9, s9, 0
	s_cmp_gt_u32 s71, 13
	s_cbranch_scc0 .LBB0_437
	s_add_u32 s4, s28, 0x2f41000
	s_addc_u32 s5, s29, 0
	s_lshl_b32 s0, s16, 8
	s_add_i32 s64, s64, s0
	v_or_b32_e32 v130, s64, v140
	v_mov_b32_e32 v131, 0
	v_lshl_add_u64 v[132:133], v[130:131], 2, s[4:5]
	global_load_dword v149, v[132:133], off
	v_lshl_or_b32 v134, v138, 2, s59
	v_mov_b32_e32 v148, 0x358637bd
	s_lshl_b32 s13, s15, 8
	s_mov_b32 s6, 0x800000
	s_movk_i32 s0, 0x36c
	v_or_b32_e32 v146, s13, v134
	s_and_b32 s9, s13, 0x300
	v_mov_b32_e32 v150, s13
	s_lshl_b32 s13, s64, 2
	v_mov_b32_e32 v142, 0x80
	s_movk_i32 s10, 0xec
	v_lshlrev_b32_e32 v138, 1, v134
	v_bitop3_b32 v134, v134, s0, v150 bitop3:0xc8
	s_and_b32 s0, s13, 0xfffffc00
	v_bitop3_b32 v154, v146, s10, v142 bitop3:0xc8
	s_or_b32 s10, s0, s9
	s_mov_b32 s1, 0x4880000
	s_cmp_gt_u32 s15, 3
	v_mov_b32_e32 v136, 0xcf
	s_mov_b32 s2, 0x2b00000
	s_cselect_b32 s0, s1, 0x4080000
	s_movk_i32 s3, 0x37c
	s_movk_i32 s8, 0x3ec
	v_bitop3_b32 v152, s64, v136, v140 bitop3:0xc8
	s_cselect_b32 s1, s2, 0x2700000
	s_add_u32 s2, s26, s0
	v_bitop3_b32 v136, v146, s3, 16 bitop3:0xc8
	v_bitop3_b32 v153, v146, s8, v142 bitop3:0xc8
	v_or_b32_e32 v152, s10, v152
	s_addc_u32 s3, s27, 0
	s_movk_i32 s7, 0x7c
	s_movk_i32 s11, 0x3fc
	v_mov_b32_e32 v144, 0x90
	s_movk_i32 s12, 0xfc
	v_lshlrev_b64 v[150:151], 12, v[130:131]
	v_lshlrev_b32_e32 v142, 2, v153
	v_ashrrev_i32_e32 v153, 31, v152
	s_add_u32 s0, s28, s1
	v_mov_b32_e32 v147, v131
	v_bitop3_b32 v140, v146, s7, 16 bitop3:0xc8
	v_bitop3_b32 v155, v146, s11, v144 bitop3:0xc8
	v_bitop3_b32 v167, v146, s12, v144 bitop3:0xc8
	v_lshlrev_b32_e32 v146, 2, v134
	v_lshlrev_b64 v[152:153], 9, v[152:153]
	v_lshl_add_u64 v[150:151], s[2:3], 0, v[150:151]
	s_addc_u32 s1, s29, 0
	v_mov_b32_e32 v139, v131
	v_lshlrev_b32_e32 v144, 2, v136
	v_lshlrev_b32_e32 v134, 1, v140
	v_lshlrev_b32_e32 v136, 1, v154
	v_lshlrev_b32_e32 v140, 2, v155
	v_lshl_add_u64 v[154:155], v[150:151], 0, v[146:147]
	v_lshl_add_u64 v[152:153], s[0:1], 0, v[152:153]
	v_mov_b32_e32 v145, v131
	v_mov_b32_e32 v135, v131
	v_mov_b32_e32 v143, v131
	v_mov_b32_e32 v137, v131
	v_lshl_add_u64 v[156:157], v[150:151], 0, v[144:145]
	v_lshl_add_u64 v[162:163], v[152:153], 0, v[134:135]
	v_mov_b32_e32 v141, v131
	v_lshl_add_u64 v[158:159], v[150:151], 0, v[142:143]
	v_lshl_add_u64 v[164:165], v[152:153], 0, v[136:137]
	v_lshl_add_u64 v[150:151], v[150:151], 0, v[140:141]
	s_movk_i32 s7, 0xdf
	s_movk_i32 s8, 0xef
	s_cmpk_lt_u32 s14, 0x100
	s_waitcnt vmcnt(0)
	v_fmamk_f32 v149, v149, 0x3a800000, v148
	v_mul_f32_e32 v160, 0x4b800000, v149
	v_cmp_gt_f32_e32 vcc, s6, v149
	s_nop 1
	v_cndmask_b32_e32 v149, v149, v160, vcc
	v_rsq_f32_e32 v149, v149
	v_lshl_add_u64 v[160:161], v[152:153], 0, v[138:139]
	v_mul_f32_e32 v166, 0x45800000, v149
	v_cndmask_b32_e32 v166, v149, v166, vcc
	v_pk_mul_f32 v[126:127], v[126:127], v[166:167] op_sel_hi:[1,0]
	v_pk_mul_f32 v[124:125], v[124:125], v[166:167] op_sel_hi:[1,0]
	v_pk_mul_f32 v[120:121], v[120:121], v[166:167] op_sel_hi:[1,0]
	global_store_dwordx4 v[154:155], v[124:127], off
	v_pk_mul_f32 v[122:123], v[122:123], v[166:167] op_sel_hi:[1,0]
	v_pk_mul_f32 v[116:117], v[116:117], v[166:167] op_sel_hi:[1,0]
	v_cvt_pk_bf16_f32 v124, v124, v125
	v_cvt_pk_bf16_f32 v125, v126, v127
	global_store_dwordx2 v[160:161], v[124:125], off
	global_store_dwordx4 v[156:157], v[120:123], off
	v_pk_mul_f32 v[118:119], v[118:119], v[166:167] op_sel_hi:[1,0]
	v_pk_mul_f32 v[112:113], v[112:113], v[166:167] op_sel_hi:[1,0]
	v_cvt_pk_bf16_f32 v120, v120, v121
	v_cvt_pk_bf16_f32 v121, v122, v123
	global_store_dwordx2 v[162:163], v[120:121], off
	global_store_dwordx4 v[158:159], v[116:119], off
	v_pk_mul_f32 v[114:115], v[114:115], v[166:167] op_sel_hi:[1,0]
	v_bitop3_b32 v120, v130, s7, 16 bitop3:0xc8
	v_cvt_pk_bf16_f32 v116, v116, v117
	v_cvt_pk_bf16_f32 v117, v118, v119
	global_store_dwordx2 v[164:165], v[116:117], off
	global_store_dwordx4 v[150:151], v[112:115], off
	v_cvt_pk_bf16_f32 v116, v112, v113
	v_cvt_pk_bf16_f32 v117, v114, v115
	v_or_b32_e32 v120, s10, v120
	v_ashrrev_i32_e32 v121, 31, v120
	v_lshlrev_b32_e32 v112, 1, v167
	v_mov_b32_e32 v113, v131
	v_lshl_add_u64 v[114:115], v[152:153], 0, v[112:113]
	global_store_dwordx2 v[114:115], v[116:117], off
	v_or_b32_e32 v114, 16, v130
	v_mov_b32_e32 v115, v131
	v_lshl_add_u64 v[116:117], v[114:115], 2, s[4:5]
	global_load_dword v149, v[116:117], off
	v_lshlrev_b64 v[114:115], 12, v[114:115]
	v_lshlrev_b64 v[120:121], 9, v[120:121]
	v_lshl_add_u64 v[114:115], s[2:3], 0, v[114:115]
	v_lshl_add_u64 v[122:123], v[114:115], 0, v[146:147]
	v_lshl_add_u64 v[120:121], s[0:1], 0, v[120:121]
	v_lshl_add_u64 v[150:151], v[120:121], 0, v[138:139]
	v_lshl_add_u64 v[124:125], v[114:115], 0, v[144:145]
	v_mov_b32_e32 v117, v131
	v_or_b32_e32 v116, 32, v130
	v_lshl_add_u64 v[126:127], v[114:115], 0, v[142:143]
	v_lshl_add_u64 v[154:155], v[120:121], 0, v[136:137]
	v_lshl_add_u64 v[118:119], v[116:117], 2, s[4:5]
	v_lshl_add_u64 v[114:115], v[114:115], 0, v[140:141]
	s_waitcnt vmcnt(0)
	v_fmamk_f32 v149, v149, 0x3a800000, v148
	v_mul_f32_e32 v152, 0x4b800000, v149
	v_cmp_gt_f32_e32 vcc, s6, v149
	s_nop 1
	v_cndmask_b32_e32 v149, v149, v152, vcc
	v_rsq_f32_e32 v149, v149
	v_lshl_add_u64 v[152:153], v[120:121], 0, v[134:135]
	v_lshl_add_u64 v[120:121], v[120:121], 0, v[112:113]
	v_mul_f32_e32 v156, 0x45800000, v149
	v_cndmask_b32_e32 v156, v149, v156, vcc
	v_pk_mul_f32 v[110:111], v[110:111], v[156:157] op_sel_hi:[1,0]
	v_pk_mul_f32 v[108:109], v[108:109], v[156:157] op_sel_hi:[1,0]
	v_pk_mul_f32 v[104:105], v[104:105], v[156:157] op_sel_hi:[1,0]
	global_store_dwordx4 v[122:123], v[108:111], off
	v_pk_mul_f32 v[106:107], v[106:107], v[156:157] op_sel_hi:[1,0]
	v_pk_mul_f32 v[100:101], v[100:101], v[156:157] op_sel_hi:[1,0]
	v_cvt_pk_bf16_f32 v108, v108, v109
	v_cvt_pk_bf16_f32 v109, v110, v111
	global_store_dwordx2 v[150:151], v[108:109], off
	global_store_dwordx4 v[124:125], v[104:107], off
	v_pk_mul_f32 v[102:103], v[102:103], v[156:157] op_sel_hi:[1,0]
	v_pk_mul_f32 v[96:97], v[96:97], v[156:157] op_sel_hi:[1,0]
	v_cvt_pk_bf16_f32 v104, v104, v105
	v_cvt_pk_bf16_f32 v105, v106, v107
	global_store_dwordx2 v[152:153], v[104:105], off
	global_store_dwordx4 v[126:127], v[100:103], off
	v_pk_mul_f32 v[98:99], v[98:99], v[156:157] op_sel_hi:[1,0]
	s_nop 0
	v_cvt_pk_bf16_f32 v100, v100, v101
	v_cvt_pk_bf16_f32 v101, v102, v103
	global_store_dwordx2 v[154:155], v[100:101], off
	global_store_dwordx4 v[114:115], v[96:99], off
	v_bitop3_b32 v102, v130, s8, 32 bitop3:0xc8
	v_or_b32_e32 v102, s10, v102
	v_cvt_pk_bf16_f32 v96, v96, v97
	v_cvt_pk_bf16_f32 v97, v98, v99
	global_store_dwordx2 v[120:121], v[96:97], off
	global_load_dword v114, v[118:119], off
	v_lshlrev_b64 v[98:99], 12, v[116:117]
	v_ashrrev_i32_e32 v103, 31, v102
	v_lshlrev_b64 v[102:103], 9, v[102:103]
	v_lshl_add_u64 v[98:99], s[2:3], 0, v[98:99]
	v_lshl_add_u64 v[104:105], v[98:99], 0, v[146:147]
	v_lshl_add_u64 v[102:103], s[0:1], 0, v[102:103]
	v_lshl_add_u64 v[110:111], v[102:103], 0, v[138:139]
	v_lshl_add_u64 v[106:107], v[98:99], 0, v[144:145]
	v_mov_b32_e32 v97, v131
	v_or_b32_e32 v96, 48, v130
	v_lshl_add_u64 v[108:109], v[98:99], 0, v[142:143]
	v_lshl_add_u64 v[116:117], v[102:103], 0, v[136:137]
	v_lshl_add_u64 v[100:101], v[96:97], 2, s[4:5]
	v_lshl_add_u64 v[98:99], v[98:99], 0, v[140:141]
	s_movk_i32 s4, 0xff
	s_movk_i32 s5, 0xcf
	s_waitcnt vmcnt(0)
	v_fmamk_f32 v114, v114, 0x3a800000, v148
	v_mul_f32_e32 v115, 0x4b800000, v114
	v_cmp_gt_f32_e32 vcc, s6, v114
	s_nop 1
	v_cndmask_b32_e32 v114, v114, v115, vcc
	v_rsq_f32_e32 v118, v114
	v_lshl_add_u64 v[114:115], v[102:103], 0, v[134:135]
	v_lshl_add_u64 v[102:103], v[102:103], 0, v[112:113]
	v_mul_f32_e32 v119, 0x45800000, v118
	v_cndmask_b32_e32 v118, v118, v119, vcc
	v_pk_mul_f32 v[94:95], v[94:95], v[118:119] op_sel_hi:[1,0]
	v_pk_mul_f32 v[92:93], v[92:93], v[118:119] op_sel_hi:[1,0]
	v_pk_mul_f32 v[88:89], v[88:89], v[118:119] op_sel_hi:[1,0]
	global_store_dwordx4 v[104:105], v[92:95], off
	v_pk_mul_f32 v[90:91], v[90:91], v[118:119] op_sel_hi:[1,0]
	v_pk_mul_f32 v[84:85], v[84:85], v[118:119] op_sel_hi:[1,0]
	v_cvt_pk_bf16_f32 v92, v92, v93
	v_cvt_pk_bf16_f32 v93, v94, v95
	global_store_dwordx2 v[110:111], v[92:93], off
	global_store_dwordx4 v[106:107], v[88:91], off
	v_pk_mul_f32 v[86:87], v[86:87], v[118:119] op_sel_hi:[1,0]
	v_pk_mul_f32 v[80:81], v[80:81], v[118:119] op_sel_hi:[1,0]
	v_cvt_pk_bf16_f32 v88, v88, v89
	v_cvt_pk_bf16_f32 v89, v90, v91
	global_store_dwordx2 v[114:115], v[88:89], off
	global_store_dwordx4 v[108:109], v[84:87], off
	v_pk_mul_f32 v[82:83], v[82:83], v[118:119] op_sel_hi:[1,0]
	s_nop 0
	v_cvt_pk_bf16_f32 v84, v84, v85
	v_cvt_pk_bf16_f32 v85, v86, v87
	global_store_dwordx2 v[116:117], v[84:85], off
	global_store_dwordx4 v[98:99], v[80:83], off
	s_nop 1
	v_cvt_pk_bf16_f32 v80, v80, v81
	v_cvt_pk_bf16_f32 v81, v82, v83
	global_store_dwordx2 v[102:103], v[80:81], off
	global_load_dword v92, v[100:101], off
	v_lshlrev_b64 v[80:81], 12, v[96:97]
	v_bitop3_b32 v82, v130, s4, 48 bitop3:0xc8
	v_or_b32_e32 v82, s10, v82
	v_ashrrev_i32_e32 v83, 31, v82
	v_lshlrev_b64 v[82:83], 9, v[82:83]
	v_lshl_add_u64 v[80:81], s[2:3], 0, v[80:81]
	v_lshl_add_u64 v[84:85], v[80:81], 0, v[146:147]
	v_lshl_add_u64 v[82:83], s[0:1], 0, v[82:83]
	v_lshl_add_u64 v[90:91], v[82:83], 0, v[138:139]
	v_lshl_add_u64 v[86:87], v[80:81], 0, v[144:145]
	v_lshl_add_u64 v[88:89], v[80:81], 0, v[142:143]
	v_lshl_add_u64 v[94:95], v[82:83], 0, v[136:137]
	v_lshl_add_u64 v[80:81], v[80:81], 0, v[140:141]
	s_waitcnt vmcnt(0)
	v_fmamk_f32 v92, v92, 0x3a800000, v148
	v_mul_f32_e32 v93, 0x4b800000, v92
	v_cmp_gt_f32_e32 vcc, s6, v92
	s_nop 1
	v_cndmask_b32_e32 v92, v92, v93, vcc
	v_rsq_f32_e32 v96, v92
	v_lshl_add_u64 v[92:93], v[82:83], 0, v[134:135]
	v_lshl_add_u64 v[82:83], v[82:83], 0, v[112:113]
	v_mul_f32_e32 v97, 0x45800000, v96
	v_cndmask_b32_e32 v96, v96, v97, vcc
	v_pk_mul_f32 v[78:79], v[78:79], v[96:97] op_sel_hi:[1,0]
	v_pk_mul_f32 v[76:77], v[76:77], v[96:97] op_sel_hi:[1,0]
	v_pk_mul_f32 v[72:73], v[72:73], v[96:97] op_sel_hi:[1,0]
	global_store_dwordx4 v[84:85], v[76:79], off
	v_pk_mul_f32 v[74:75], v[74:75], v[96:97] op_sel_hi:[1,0]
	v_pk_mul_f32 v[68:69], v[68:69], v[96:97] op_sel_hi:[1,0]
	v_cvt_pk_bf16_f32 v76, v76, v77
	v_cvt_pk_bf16_f32 v77, v78, v79
	global_store_dwordx2 v[90:91], v[76:77], off
	global_store_dwordx4 v[86:87], v[72:75], off
	v_pk_mul_f32 v[70:71], v[70:71], v[96:97] op_sel_hi:[1,0]
	v_pk_mul_f32 v[64:65], v[64:65], v[96:97] op_sel_hi:[1,0]
	v_cvt_pk_bf16_f32 v72, v72, v73
	v_cvt_pk_bf16_f32 v73, v74, v75
	global_store_dwordx2 v[92:93], v[72:73], off
	global_store_dwordx4 v[88:89], v[68:71], off
	v_pk_mul_f32 v[66:67], v[66:67], v[96:97] op_sel_hi:[1,0]
	s_nop 0
	v_cvt_pk_bf16_f32 v68, v68, v69
	v_cvt_pk_bf16_f32 v69, v70, v71
	global_store_dwordx2 v[94:95], v[68:69], off
	global_store_dwordx4 v[80:81], v[64:67], off
	s_nop 1
	v_cvt_pk_bf16_f32 v64, v64, v65
	v_cvt_pk_bf16_f32 v65, v66, v67
	global_store_dwordx2 v[82:83], v[64:65], off
	global_load_dword v76, v[132:133], off offset:512
	v_add_u32_e32 v64, 0x80, v130
	v_mov_b32_e32 v65, v131
	v_lshlrev_b32_e32 v68, 2, v64
	v_lshlrev_b64 v[66:67], 12, v[64:65]
	v_and_b32_e32 v65, 0xfffffc00, v68
	v_or_b32_e32 v81, s9, v65
	v_and_or_b32 v64, v64, s5, v81
	v_ashrrev_i32_e32 v65, 31, v64
	v_lshlrev_b64 v[64:65], 9, v[64:65]
	v_lshl_add_u64 v[66:67], s[2:3], 0, v[66:67]
	v_lshl_add_u64 v[68:69], v[66:67], 0, v[146:147]
	v_lshl_add_u64 v[64:65], s[0:1], 0, v[64:65]
	v_lshl_add_u64 v[74:75], v[64:65], 0, v[138:139]
	v_lshl_add_u64 v[70:71], v[66:67], 0, v[144:145]
	v_lshl_add_u64 v[72:73], v[66:67], 0, v[142:143]
	v_lshl_add_u64 v[78:79], v[64:65], 0, v[136:137]
	v_lshl_add_u64 v[66:67], v[66:67], 0, v[140:141]
	s_waitcnt vmcnt(0)
	v_fmamk_f32 v76, v76, 0x3a800000, v148
	v_mul_f32_e32 v77, 0x4b800000, v76
	v_cmp_gt_f32_e32 vcc, s6, v76
	s_nop 1
	v_cndmask_b32_e32 v76, v76, v77, vcc
	v_rsq_f32_e32 v80, v76
	v_lshl_add_u64 v[76:77], v[64:65], 0, v[134:135]
	v_lshl_add_u64 v[64:65], v[64:65], 0, v[112:113]
	v_mul_f32_e32 v82, 0x45800000, v80
	v_cndmask_b32_e32 v80, v80, v82, vcc
	v_pk_mul_f32 v[62:63], v[62:63], v[80:81] op_sel_hi:[1,0]
	v_pk_mul_f32 v[60:61], v[60:61], v[80:81] op_sel_hi:[1,0]
	v_pk_mul_f32 v[56:57], v[56:57], v[80:81] op_sel_hi:[1,0]
	global_store_dwordx4 v[68:69], v[60:63], off
	v_pk_mul_f32 v[58:59], v[58:59], v[80:81] op_sel_hi:[1,0]
	v_pk_mul_f32 v[52:53], v[52:53], v[80:81] op_sel_hi:[1,0]
	v_cvt_pk_bf16_f32 v60, v60, v61
	v_cvt_pk_bf16_f32 v61, v62, v63
	global_store_dwordx2 v[74:75], v[60:61], off
	global_store_dwordx4 v[70:71], v[56:59], off
	v_pk_mul_f32 v[54:55], v[54:55], v[80:81] op_sel_hi:[1,0]
	v_pk_mul_f32 v[48:49], v[48:49], v[80:81] op_sel_hi:[1,0]
	v_cvt_pk_bf16_f32 v56, v56, v57
	v_cvt_pk_bf16_f32 v57, v58, v59
	global_store_dwordx2 v[76:77], v[56:57], off
	global_store_dwordx4 v[72:73], v[52:55], off
	v_pk_mul_f32 v[50:51], v[50:51], v[80:81] op_sel_hi:[1,0]
	s_nop 0
	v_cvt_pk_bf16_f32 v52, v52, v53
	v_cvt_pk_bf16_f32 v53, v54, v55
	global_store_dwordx2 v[78:79], v[52:53], off
	global_store_dwordx4 v[66:67], v[48:51], off
	s_nop 1
	v_cvt_pk_bf16_f32 v48, v48, v49
	v_cvt_pk_bf16_f32 v49, v50, v51
	global_store_dwordx2 v[64:65], v[48:49], off
	global_load_dword v60, v[132:133], off offset:576
	v_mov_b32_e32 v49, v131
	v_add_u32_e32 v48, 0x90, v130
	v_lshlrev_b64 v[50:51], 12, v[48:49]
	v_and_or_b32 v48, v48, s7, v81
	v_ashrrev_i32_e32 v49, 31, v48
	v_lshlrev_b64 v[48:49], 9, v[48:49]
	v_lshl_add_u64 v[50:51], s[2:3], 0, v[50:51]
	v_lshl_add_u64 v[52:53], v[50:51], 0, v[146:147]
	v_lshl_add_u64 v[48:49], s[0:1], 0, v[48:49]
	v_lshl_add_u64 v[58:59], v[48:49], 0, v[138:139]
	v_lshl_add_u64 v[54:55], v[50:51], 0, v[144:145]
	v_lshl_add_u64 v[56:57], v[50:51], 0, v[142:143]
	v_lshl_add_u64 v[62:63], v[48:49], 0, v[136:137]
	v_lshl_add_u64 v[50:51], v[50:51], 0, v[140:141]
	s_waitcnt vmcnt(0)
	v_fmamk_f32 v60, v60, 0x3a800000, v148
	v_mul_f32_e32 v61, 0x4b800000, v60
	v_cmp_gt_f32_e32 vcc, s6, v60
	s_nop 1
	v_cndmask_b32_e32 v60, v60, v61, vcc
	v_rsq_f32_e32 v64, v60
	v_lshl_add_u64 v[60:61], v[48:49], 0, v[134:135]
	v_lshl_add_u64 v[48:49], v[48:49], 0, v[112:113]
	v_mul_f32_e32 v65, 0x45800000, v64
	v_cndmask_b32_e32 v64, v64, v65, vcc
	v_pk_mul_f32 v[46:47], v[46:47], v[64:65] op_sel_hi:[1,0]
	v_pk_mul_f32 v[44:45], v[44:45], v[64:65] op_sel_hi:[1,0]
	v_pk_mul_f32 v[40:41], v[40:41], v[64:65] op_sel_hi:[1,0]
	global_store_dwordx4 v[52:53], v[44:47], off
	v_pk_mul_f32 v[42:43], v[42:43], v[64:65] op_sel_hi:[1,0]
	v_pk_mul_f32 v[36:37], v[36:37], v[64:65] op_sel_hi:[1,0]
	v_cvt_pk_bf16_f32 v44, v44, v45
	v_cvt_pk_bf16_f32 v45, v46, v47
	global_store_dwordx2 v[58:59], v[44:45], off
	global_store_dwordx4 v[54:55], v[40:43], off
	v_pk_mul_f32 v[38:39], v[38:39], v[64:65] op_sel_hi:[1,0]
	v_pk_mul_f32 v[32:33], v[32:33], v[64:65] op_sel_hi:[1,0]
	v_cvt_pk_bf16_f32 v40, v40, v41
	v_cvt_pk_bf16_f32 v41, v42, v43
	global_store_dwordx2 v[60:61], v[40:41], off
	global_store_dwordx4 v[56:57], v[36:39], off
	v_pk_mul_f32 v[34:35], v[34:35], v[64:65] op_sel_hi:[1,0]
	s_nop 0
	v_cvt_pk_bf16_f32 v36, v36, v37
	v_cvt_pk_bf16_f32 v37, v38, v39
	global_store_dwordx2 v[62:63], v[36:37], off
	global_store_dwordx4 v[50:51], v[32:35], off
	s_nop 1
	v_cvt_pk_bf16_f32 v32, v32, v33
	v_cvt_pk_bf16_f32 v33, v34, v35
	global_store_dwordx2 v[48:49], v[32:33], off
	global_load_dword v44, v[132:133], off offset:640
	v_mov_b32_e32 v33, v131
	v_add_u32_e32 v32, 0xa0, v130
	v_lshlrev_b64 v[34:35], 12, v[32:33]
	v_and_or_b32 v32, v32, s8, v81
	v_ashrrev_i32_e32 v33, 31, v32
	v_lshlrev_b64 v[32:33], 9, v[32:33]
	v_lshl_add_u64 v[34:35], s[2:3], 0, v[34:35]
	v_lshl_add_u64 v[36:37], v[34:35], 0, v[146:147]
	v_lshl_add_u64 v[32:33], s[0:1], 0, v[32:33]
	v_lshl_add_u64 v[42:43], v[32:33], 0, v[138:139]
	v_lshl_add_u64 v[38:39], v[34:35], 0, v[144:145]
	v_lshl_add_u64 v[40:41], v[34:35], 0, v[142:143]
	v_lshl_add_u64 v[46:47], v[32:33], 0, v[136:137]
	v_lshl_add_u64 v[34:35], v[34:35], 0, v[140:141]
	v_add_u32_e32 v130, 0xb0, v130
	s_waitcnt vmcnt(0)
	v_fmamk_f32 v44, v44, 0x3a800000, v148
	v_mul_f32_e32 v45, 0x4b800000, v44
	v_cmp_gt_f32_e32 vcc, s6, v44
	s_nop 1
	v_cndmask_b32_e32 v44, v44, v45, vcc
	v_rsq_f32_e32 v48, v44
	v_lshl_add_u64 v[44:45], v[32:33], 0, v[134:135]
	v_lshl_add_u64 v[32:33], v[32:33], 0, v[112:113]
	v_mul_f32_e32 v49, 0x45800000, v48
	v_cndmask_b32_e32 v48, v48, v49, vcc
	v_pk_mul_f32 v[30:31], v[30:31], v[48:49] op_sel_hi:[1,0]
	v_pk_mul_f32 v[28:29], v[28:29], v[48:49] op_sel_hi:[1,0]
	v_pk_mul_f32 v[24:25], v[24:25], v[48:49] op_sel_hi:[1,0]
	global_store_dwordx4 v[36:37], v[28:31], off
	v_pk_mul_f32 v[26:27], v[26:27], v[48:49] op_sel_hi:[1,0]
	v_pk_mul_f32 v[20:21], v[20:21], v[48:49] op_sel_hi:[1,0]
	v_cvt_pk_bf16_f32 v28, v28, v29
	v_cvt_pk_bf16_f32 v29, v30, v31
	global_store_dwordx2 v[42:43], v[28:29], off
	global_store_dwordx4 v[38:39], v[24:27], off
	v_pk_mul_f32 v[22:23], v[22:23], v[48:49] op_sel_hi:[1,0]
	v_pk_mul_f32 v[16:17], v[16:17], v[48:49] op_sel_hi:[1,0]
	v_cvt_pk_bf16_f32 v24, v24, v25
	v_cvt_pk_bf16_f32 v25, v26, v27
	global_store_dwordx2 v[44:45], v[24:25], off
	global_store_dwordx4 v[40:41], v[20:23], off
	v_pk_mul_f32 v[18:19], v[18:19], v[48:49] op_sel_hi:[1,0]
	s_nop 0
	v_cvt_pk_bf16_f32 v20, v20, v21
	v_cvt_pk_bf16_f32 v21, v22, v23
	global_store_dwordx2 v[46:47], v[20:21], off
	global_store_dwordx4 v[34:35], v[16:19], off
	s_nop 1
	v_cvt_pk_bf16_f32 v16, v16, v17
	v_cvt_pk_bf16_f32 v17, v18, v19
	global_store_dwordx2 v[32:33], v[16:17], off
	global_load_dword v28, v[132:133], off offset:704
	v_and_or_b32 v18, v130, s4, v81
	v_lshlrev_b64 v[16:17], 12, v[130:131]
	v_ashrrev_i32_e32 v19, 31, v18
	v_lshlrev_b64 v[18:19], 9, v[18:19]
	v_lshl_add_u64 v[16:17], s[2:3], 0, v[16:17]
	v_lshl_add_u64 v[20:21], v[16:17], 0, v[146:147]
	v_lshl_add_u64 v[18:19], s[0:1], 0, v[18:19]
	v_lshl_add_u64 v[26:27], v[18:19], 0, v[138:139]
	v_lshl_add_u64 v[22:23], v[16:17], 0, v[144:145]
	v_lshl_add_u64 v[24:25], v[16:17], 0, v[142:143]
	v_lshl_add_u64 v[30:31], v[18:19], 0, v[136:137]
	v_lshl_add_u64 v[16:17], v[16:17], 0, v[140:141]
	s_waitcnt vmcnt(0)
	v_fmac_f32_e32 v148, 0x3a800000, v28
	v_mul_f32_e32 v28, 0x4b800000, v148
	v_cmp_gt_f32_e32 vcc, s6, v148
	s_nop 1
	v_cndmask_b32_e32 v28, v148, v28, vcc
	v_rsq_f32_e32 v32, v28
	v_lshl_add_u64 v[28:29], v[18:19], 0, v[134:135]
	v_lshl_add_u64 v[18:19], v[18:19], 0, v[112:113]
	v_mul_f32_e32 v33, 0x45800000, v32
	v_cndmask_b32_e32 v32, v32, v33, vcc
	v_pk_mul_f32 v[14:15], v[14:15], v[32:33] op_sel_hi:[1,0]
	v_pk_mul_f32 v[12:13], v[12:13], v[32:33] op_sel_hi:[1,0]
	v_pk_mul_f32 v[8:9], v[8:9], v[32:33] op_sel_hi:[1,0]
	global_store_dwordx4 v[20:21], v[12:15], off
	v_pk_mul_f32 v[10:11], v[10:11], v[32:33] op_sel_hi:[1,0]
	v_pk_mul_f32 v[4:5], v[4:5], v[32:33] op_sel_hi:[1,0]
	v_cvt_pk_bf16_f32 v12, v12, v13
	v_cvt_pk_bf16_f32 v13, v14, v15
	global_store_dwordx2 v[26:27], v[12:13], off
	global_store_dwordx4 v[22:23], v[8:11], off
	v_pk_mul_f32 v[6:7], v[6:7], v[32:33] op_sel_hi:[1,0]
	v_pk_mul_f32 v[0:1], v[0:1], v[32:33] op_sel_hi:[1,0]
	v_cvt_pk_bf16_f32 v8, v8, v9
	v_cvt_pk_bf16_f32 v9, v10, v11
	global_store_dwordx2 v[28:29], v[8:9], off
	global_store_dwordx4 v[24:25], v[4:7], off
	v_pk_mul_f32 v[2:3], v[2:3], v[32:33] op_sel_hi:[1,0]
	s_nop 0
	v_cvt_pk_bf16_f32 v4, v4, v5
	v_cvt_pk_bf16_f32 v5, v6, v7
	global_store_dwordx2 v[30:31], v[4:5], off
	global_store_dwordx4 v[16:17], v[0:3], off
	s_nop 1
	v_cvt_pk_bf16_f32 v0, v0, v1
	v_cvt_pk_bf16_f32 v1, v2, v3
	global_store_dwordx2 v[18:19], v[0:1], off
	s_waitcnt vmcnt(0)
	s_cbranch_scc0 .LBB0_440
	s_barrier

.LBB0_990:
	ds_read_b128 v[146:149], v155
	ds_read_b128 v[160:163], v155 offset:1024
	ds_read_b128 v[164:167], v155 offset:2048
	ds_read_b128 v[168:171], v155 offset:3072
	ds_read_b128 v[172:175], v156
	ds_read_b128 v[176:179], v156 offset:1024
	ds_read_b128 v[180:183], v156 offset:2048
	ds_read_b128 v[184:187], v156 offset:3072
	s_add_u32 s23, s54, 0xfffc0080
	s_addc_u32 s33, s55, -1
	s_cmp_eq_u32 s75, 12
	s_cselect_b32 s59, s20, s33
	s_cselect_b32 s58, s21, s23
	s_cselect_b32 s57, s19, s74
	s_cselect_b32 s56, s45, s73
	v_lshl_add_u64 v[220:221], s[54:55], 0, v[138:139]
	s_add_i32 m0, s51, 0xc000
	ds_read_b128 v[188:191], v157
	ds_read_b128 v[192:195], v157 offset:1024
	ds_read_b128 v[196:199], v157 offset:2048
	ds_read_b128 v[200:203], v157 offset:3072
	ds_read_b128 v[204:207], v157 offset:4096
	ds_read_b128 v[208:211], v157 offset:5120
	ds_read_b128 v[212:215], v157 offset:6144
	ds_read_b128 v[216:219], v157 offset:7168
	global_load_lds_dwordx4 v[220:221], off
	v_lshl_add_u64 v[220:221], s[54:55], 0, v[140:141]
	s_add_i32 m0, s51, 0xe000
	s_nop 0
	global_load_lds_dwordx4 v[220:221], off
	s_waitcnt vmcnt(8)
	s_waitcnt lgkmcnt(0)
	s_barrier
	v_mfma_f32_16x16x32_bf16 v[124:127], v[146:149], v[188:191], v[124:127]
	v_mfma_f32_16x16x32_bf16 v[120:123], v[164:167], v[188:191], v[120:123]
	v_mfma_f32_16x16x32_bf16 v[108:111], v[146:149], v[196:199], v[108:111]
	v_mfma_f32_16x16x32_bf16 v[104:107], v[164:167], v[196:199], v[104:107]
	v_mfma_f32_16x16x32_bf16 v[92:95], v[146:149], v[204:207], v[92:95]
	v_mfma_f32_16x16x32_bf16 v[88:91], v[164:167], v[204:207], v[88:91]
	v_mfma_f32_16x16x32_bf16 v[76:79], v[146:149], v[212:215], v[76:79]
	v_mfma_f32_16x16x32_bf16 v[72:75], v[164:167], v[212:215], v[72:75]
	v_mfma_f32_16x16x32_bf16 v[124:127], v[160:163], v[192:195], v[124:127]
	v_mfma_f32_16x16x32_bf16 v[120:123], v[168:171], v[192:195], v[120:123]
	v_mfma_f32_16x16x32_bf16 v[108:111], v[160:163], v[200:203], v[108:111]
	v_mfma_f32_16x16x32_bf16 v[104:107], v[168:171], v[200:203], v[104:107]
	v_mfma_f32_16x16x32_bf16 v[92:95], v[160:163], v[208:211], v[92:95]
	v_mfma_f32_16x16x32_bf16 v[88:91], v[168:171], v[208:211], v[88:91]
	v_mfma_f32_16x16x32_bf16 v[76:79], v[160:163], v[216:219], v[76:79]
	v_mfma_f32_16x16x32_bf16 v[72:75], v[168:171], v[216:219], v[72:75]
	v_mfma_f32_16x16x32_bf16 v[116:119], v[172:175], v[188:191], v[116:119]
	v_mfma_f32_16x16x32_bf16 v[112:115], v[180:183], v[188:191], v[112:115]
	v_mfma_f32_16x16x32_bf16 v[100:103], v[172:175], v[196:199], v[100:103]
	v_mfma_f32_16x16x32_bf16 v[96:99], v[180:183], v[196:199], v[96:99]
	v_mfma_f32_16x16x32_bf16 v[84:87], v[172:175], v[204:207], v[84:87]
	v_mfma_f32_16x16x32_bf16 v[80:83], v[180:183], v[204:207], v[80:83]
	v_mfma_f32_16x16x32_bf16 v[68:71], v[172:175], v[212:215], v[68:71]
	v_mfma_f32_16x16x32_bf16 v[64:67], v[180:183], v[212:215], v[64:67]
	v_mfma_f32_16x16x32_bf16 v[116:119], v[176:179], v[192:195], v[116:119]
	v_mfma_f32_16x16x32_bf16 v[112:115], v[184:187], v[192:195], v[112:115]
	v_mfma_f32_16x16x32_bf16 v[100:103], v[176:179], v[200:203], v[100:103]
	v_mfma_f32_16x16x32_bf16 v[96:99], v[184:187], v[200:203], v[96:99]
	v_mfma_f32_16x16x32_bf16 v[84:87], v[176:179], v[208:211], v[84:87]
	v_mfma_f32_16x16x32_bf16 v[80:83], v[184:187], v[208:211], v[80:83]
	v_mfma_f32_16x16x32_bf16 v[68:71], v[176:179], v[216:219], v[68:71]
	v_mfma_f32_16x16x32_bf16 v[64:67], v[184:187], v[216:219], v[64:67]
	s_barrier
	s_add_i32 s23, s71, s62
	v_lshl_add_u64 v[220:221], s[56:57], 0, v[132:133]
	s_mov_b32 m0, s23
	ds_read_b128 v[188:191], v157 offset:16384
	ds_read_b128 v[192:195], v157 offset:17408
	ds_read_b128 v[196:199], v157 offset:18432
	ds_read_b128 v[200:203], v157 offset:19456
	ds_read_b128 v[204:207], v157 offset:20480
	ds_read_b128 v[208:211], v157 offset:21504
	ds_read_b128 v[212:215], v157 offset:22528
	ds_read_b128 v[216:219], v157 offset:23552
	global_load_lds_dwordx4 v[220:221], off
	s_add_i32 m0, s23, 0x2000
	s_add_u32 s76, s56, 0x40000
	v_lshl_add_u64 v[222:223], s[56:57], 0, v[136:137]
	s_addc_u32 s77, s57, 0
	s_add_i32 s23, s72, s62
	global_load_lds_dwordx4 v[222:223], off
	v_lshl_add_u64 v[224:225], s[76:77], 0, v[132:133]
	s_mov_b32 m0, s23
	v_lshl_add_u64 v[226:227], s[58:59], 0, v[134:135]
	global_load_lds_dwordx4 v[224:225], off
	v_lshl_add_u64 v[224:225], s[76:77], 0, v[136:137]
	s_add_i32 m0, s23, 0x2000
	s_nop 0
	global_load_lds_dwordx4 v[224:225], off
	v_lshl_add_u64 v[224:225], s[58:59], 0, v[130:131]
	s_mov_b32 m0, s51
	s_nop 0
	global_load_lds_dwordx4 v[224:225], off
	s_mov_b32 m0, s53
	s_nop 0
	global_load_lds_dwordx4 v[226:227], off
	s_waitcnt vmcnt(8)
	s_waitcnt lgkmcnt(0)
	s_barrier
	v_mfma_f32_16x16x32_bf16 v[60:63], v[146:149], v[188:191], v[60:63]
	v_mfma_f32_16x16x32_bf16 v[56:59], v[164:167], v[188:191], v[56:59]
	v_mfma_f32_16x16x32_bf16 v[44:47], v[146:149], v[196:199], v[44:47]
	v_mfma_f32_16x16x32_bf16 v[40:43], v[164:167], v[196:199], v[40:43]
	v_mfma_f32_16x16x32_bf16 v[28:31], v[146:149], v[204:207], v[28:31]
	v_mfma_f32_16x16x32_bf16 v[24:27], v[164:167], v[204:207], v[24:27]
	v_mfma_f32_16x16x32_bf16 v[12:15], v[146:149], v[212:215], v[12:15]
	v_mfma_f32_16x16x32_bf16 v[8:11], v[164:167], v[212:215], v[8:11]
	v_mfma_f32_16x16x32_bf16 v[60:63], v[160:163], v[192:195], v[60:63]
	v_mfma_f32_16x16x32_bf16 v[56:59], v[168:171], v[192:195], v[56:59]
	v_mfma_f32_16x16x32_bf16 v[44:47], v[160:163], v[200:203], v[44:47]
	v_mfma_f32_16x16x32_bf16 v[40:43], v[168:171], v[200:203], v[40:43]
	v_mfma_f32_16x16x32_bf16 v[28:31], v[160:163], v[208:211], v[28:31]
	v_mfma_f32_16x16x32_bf16 v[24:27], v[168:171], v[208:211], v[24:27]
	v_mfma_f32_16x16x32_bf16 v[12:15], v[160:163], v[216:219], v[12:15]
	v_mfma_f32_16x16x32_bf16 v[8:11], v[168:171], v[216:219], v[8:11]
	v_mfma_f32_16x16x32_bf16 v[52:55], v[172:175], v[188:191], v[52:55]
	v_mfma_f32_16x16x32_bf16 v[48:51], v[180:183], v[188:191], v[48:51]
	v_mfma_f32_16x16x32_bf16 v[36:39], v[172:175], v[196:199], v[36:39]
	v_mfma_f32_16x16x32_bf16 v[32:35], v[180:183], v[196:199], v[32:35]
	v_mfma_f32_16x16x32_bf16 v[20:23], v[172:175], v[204:207], v[20:23]
	v_mfma_f32_16x16x32_bf16 v[16:19], v[180:183], v[204:207], v[16:19]
	v_mfma_f32_16x16x32_bf16 v[4:7], v[172:175], v[212:215], v[4:7]
	v_mfma_f32_16x16x32_bf16 v[0:3], v[180:183], v[212:215], v[0:3]
	v_mfma_f32_16x16x32_bf16 v[52:55], v[176:179], v[192:195], v[52:55]
	v_mfma_f32_16x16x32_bf16 v[48:51], v[184:187], v[192:195], v[48:51]
	v_mfma_f32_16x16x32_bf16 v[36:39], v[176:179], v[200:203], v[36:39]
	v_mfma_f32_16x16x32_bf16 v[32:35], v[184:187], v[200:203], v[32:35]
	v_mfma_f32_16x16x32_bf16 v[20:23], v[176:179], v[208:211], v[20:23]
	v_mfma_f32_16x16x32_bf16 v[16:19], v[184:187], v[208:211], v[16:19]
	v_mfma_f32_16x16x32_bf16 v[4:7], v[176:179], v[216:219], v[4:7]
	v_mfma_f32_16x16x32_bf16 v[0:3], v[184:187], v[216:219], v[0:3]
	s_barrier
	s_add_i32 s23, 0, 0x18000
	v_add_u32_e32 v159, s23, v153
	s_add_i32 s33, 0, 0x1c000
	ds_read_b128 v[146:149], v159
	ds_read_b128 v[160:163], v159 offset:1024
	ds_read_b128 v[164:167], v159 offset:2048
	ds_read_b128 v[168:171], v159 offset:3072
	v_add_u32_e32 v159, s33, v153
	ds_read_b128 v[172:175], v159
	ds_read_b128 v[176:179], v159 offset:1024
	ds_read_b128 v[180:183], v159 offset:2048
	ds_read_b128 v[184:187], v159 offset:3072
	s_add_u32 s58, s58, 0x40000
	s_addc_u32 s59, s59, 0
	s_mov_b32 m0, s63
	v_lshl_add_u64 v[228:229], s[58:59], 0, v[130:131]
	ds_read_b128 v[188:191], v157 offset:32768
	ds_read_b128 v[192:195], v157 offset:33792
	ds_read_b128 v[196:199], v157 offset:34816
	ds_read_b128 v[200:203], v157 offset:35840
	ds_read_b128 v[204:207], v157 offset:36864
	ds_read_b128 v[208:211], v157 offset:37888
	ds_read_b128 v[212:215], v157 offset:38912
	ds_read_b128 v[216:219], v157 offset:39936
	global_load_lds_dwordx4 v[228:229], off
	v_lshl_add_u64 v[228:229], s[58:59], 0, v[134:135]
	s_mov_b32 m0, s64
	s_nop 0
	global_load_lds_dwordx4 v[228:229], off
	s_waitcnt vmcnt(8)
	s_waitcnt lgkmcnt(0)
	s_barrier
	v_mfma_f32_16x16x32_bf16 v[124:127], v[146:149], v[188:191], v[124:127]
	v_mfma_f32_16x16x32_bf16 v[120:123], v[164:167], v[188:191], v[120:123]
	v_mfma_f32_16x16x32_bf16 v[108:111], v[146:149], v[196:199], v[108:111]
	v_mfma_f32_16x16x32_bf16 v[104:107], v[164:167], v[196:199], v[104:107]
	v_mfma_f32_16x16x32_bf16 v[92:95], v[146:149], v[204:207], v[92:95]
	v_mfma_f32_16x16x32_bf16 v[88:91], v[164:167], v[204:207], v[88:91]
	v_mfma_f32_16x16x32_bf16 v[76:79], v[146:149], v[212:215], v[76:79]
	v_mfma_f32_16x16x32_bf16 v[72:75], v[164:167], v[212:215], v[72:75]
	v_mfma_f32_16x16x32_bf16 v[124:127], v[160:163], v[192:195], v[124:127]
	v_mfma_f32_16x16x32_bf16 v[120:123], v[168:171], v[192:195], v[120:123]
	v_mfma_f32_16x16x32_bf16 v[108:111], v[160:163], v[200:203], v[108:111]
	v_mfma_f32_16x16x32_bf16 v[104:107], v[168:171], v[200:203], v[104:107]
	v_mfma_f32_16x16x32_bf16 v[92:95], v[160:163], v[208:211], v[92:95]
	v_mfma_f32_16x16x32_bf16 v[88:91], v[168:171], v[208:211], v[88:91]
	v_mfma_f32_16x16x32_bf16 v[76:79], v[160:163], v[216:219], v[76:79]
	v_mfma_f32_16x16x32_bf16 v[72:75], v[168:171], v[216:219], v[72:75]
	v_mfma_f32_16x16x32_bf16 v[116:119], v[172:175], v[188:191], v[116:119]
	v_mfma_f32_16x16x32_bf16 v[112:115], v[180:183], v[188:191], v[112:115]
	v_mfma_f32_16x16x32_bf16 v[100:103], v[172:175], v[196:199], v[100:103]
	v_mfma_f32_16x16x32_bf16 v[96:99], v[180:183], v[196:199], v[96:99]
	v_mfma_f32_16x16x32_bf16 v[84:87], v[172:175], v[204:207], v[84:87]
	v_mfma_f32_16x16x32_bf16 v[80:83], v[180:183], v[204:207], v[80:83]
	v_mfma_f32_16x16x32_bf16 v[68:71], v[172:175], v[212:215], v[68:71]
	v_mfma_f32_16x16x32_bf16 v[64:67], v[180:183], v[212:215], v[64:67]
	v_mfma_f32_16x16x32_bf16 v[116:119], v[176:179], v[192:195], v[116:119]
	v_mfma_f32_16x16x32_bf16 v[112:115], v[184:187], v[192:195], v[112:115]
	v_mfma_f32_16x16x32_bf16 v[100:103], v[176:179], v[200:203], v[100:103]
	v_mfma_f32_16x16x32_bf16 v[96:99], v[184:187], v[200:203], v[96:99]
	v_mfma_f32_16x16x32_bf16 v[84:87], v[176:179], v[208:211], v[84:87]
	v_mfma_f32_16x16x32_bf16 v[80:83], v[184:187], v[208:211], v[80:83]
	v_mfma_f32_16x16x32_bf16 v[68:71], v[176:179], v[216:219], v[68:71]
	v_mfma_f32_16x16x32_bf16 v[64:67], v[184:187], v[216:219], v[64:67]
	s_barrier
	s_add_i32 s23, s23, s62
	v_lshl_add_u64 v[220:221], v[220:221], 0, s[14:15]
	s_mov_b32 m0, s23
	ds_read_b128 v[188:191], v157 offset:49152
	ds_read_b128 v[192:195], v157 offset:50176
	ds_read_b128 v[196:199], v157 offset:51200
	ds_read_b128 v[200:203], v157 offset:52224
	ds_read_b128 v[204:207], v157 offset:53248
	ds_read_b128 v[208:211], v157 offset:54272
	ds_read_b128 v[212:215], v157 offset:55296
	ds_read_b128 v[216:219], v157 offset:56320
	global_load_lds_dwordx4 v[220:221], off
	s_add_i32 m0, s23, 0x2000
	s_add_u32 s56, s56, 0x40080
	v_lshl_add_u64 v[220:221], v[222:223], 0, s[14:15]
	s_addc_u32 s57, s57, 0
	s_add_i32 s23, s33, s62
	global_load_lds_dwordx4 v[220:221], off
	v_lshl_add_u64 v[220:221], s[56:57], 0, v[132:133]
	s_mov_b32 m0, s23
	s_nop 0
	global_load_lds_dwordx4 v[220:221], off
	v_lshl_add_u64 v[220:221], s[56:57], 0, v[136:137]
	s_add_i32 m0, s23, 0x2000
	s_nop 0
	global_load_lds_dwordx4 v[220:221], off
	v_lshl_add_u64 v[220:221], v[224:225], 0, s[14:15]
	s_mov_b32 m0, s68
	s_nop 0
	global_load_lds_dwordx4 v[220:221], off
	v_lshl_add_u64 v[220:221], v[226:227], 0, s[14:15]
	s_mov_b32 m0, s69
	s_nop 0
	global_load_lds_dwordx4 v[220:221], off
	s_waitcnt vmcnt(8)
	s_waitcnt lgkmcnt(0)
	s_barrier
	v_mfma_f32_16x16x32_bf16 v[60:63], v[146:149], v[188:191], v[60:63]
	v_mfma_f32_16x16x32_bf16 v[56:59], v[164:167], v[188:191], v[56:59]
	v_mfma_f32_16x16x32_bf16 v[44:47], v[146:149], v[196:199], v[44:47]
	v_mfma_f32_16x16x32_bf16 v[40:43], v[164:167], v[196:199], v[40:43]
	v_mfma_f32_16x16x32_bf16 v[28:31], v[146:149], v[204:207], v[28:31]
	v_mfma_f32_16x16x32_bf16 v[24:27], v[164:167], v[204:207], v[24:27]
	v_mfma_f32_16x16x32_bf16 v[12:15], v[146:149], v[212:215], v[12:15]
	v_mfma_f32_16x16x32_bf16 v[8:11], v[164:167], v[212:215], v[8:11]
	v_mfma_f32_16x16x32_bf16 v[60:63], v[160:163], v[192:195], v[60:63]
	v_mfma_f32_16x16x32_bf16 v[56:59], v[168:171], v[192:195], v[56:59]
	v_mfma_f32_16x16x32_bf16 v[44:47], v[160:163], v[200:203], v[44:47]
	v_mfma_f32_16x16x32_bf16 v[40:43], v[168:171], v[200:203], v[40:43]
	v_mfma_f32_16x16x32_bf16 v[28:31], v[160:163], v[208:211], v[28:31]
	v_mfma_f32_16x16x32_bf16 v[24:27], v[168:171], v[208:211], v[24:27]
	v_mfma_f32_16x16x32_bf16 v[12:15], v[160:163], v[216:219], v[12:15]
	v_mfma_f32_16x16x32_bf16 v[8:11], v[168:171], v[216:219], v[8:11]
	v_mfma_f32_16x16x32_bf16 v[52:55], v[172:175], v[188:191], v[52:55]
	v_mfma_f32_16x16x32_bf16 v[48:51], v[180:183], v[188:191], v[48:51]
	v_mfma_f32_16x16x32_bf16 v[36:39], v[172:175], v[196:199], v[36:39]
	v_mfma_f32_16x16x32_bf16 v[32:35], v[180:183], v[196:199], v[32:35]
	v_mfma_f32_16x16x32_bf16 v[20:23], v[172:175], v[204:207], v[20:23]
	v_mfma_f32_16x16x32_bf16 v[16:19], v[180:183], v[204:207], v[16:19]
	v_mfma_f32_16x16x32_bf16 v[4:7], v[172:175], v[212:215], v[4:7]
	v_mfma_f32_16x16x32_bf16 v[0:3], v[180:183], v[212:215], v[0:3]
	v_mfma_f32_16x16x32_bf16 v[52:55], v[176:179], v[192:195], v[52:55]
	v_mfma_f32_16x16x32_bf16 v[48:51], v[184:187], v[192:195], v[48:51]
	v_mfma_f32_16x16x32_bf16 v[36:39], v[176:179], v[200:203], v[36:39]
	v_mfma_f32_16x16x32_bf16 v[32:35], v[184:187], v[200:203], v[32:35]
	v_mfma_f32_16x16x32_bf16 v[20:23], v[176:179], v[208:211], v[20:23]
	v_mfma_f32_16x16x32_bf16 v[16:19], v[184:187], v[208:211], v[16:19]
	v_mfma_f32_16x16x32_bf16 v[4:7], v[176:179], v[216:219], v[4:7]
	v_mfma_f32_16x16x32_bf16 v[0:3], v[184:187], v[216:219], v[0:3]
	s_barrier
	s_add_i32 s75, s75, 2
	s_add_u32 s54, s54, 0x100
	s_addc_u32 s55, s55, 0
	s_add_u32 s73, s73, 0x100
	s_addc_u32 s74, s74, 0
	s_cmp_gt_u32 s75, 13
	s_cbranch_scc0 .LBB0_990
	s_and_b64 vcc, exec, s[16:17]
	s_cbranch_vccz .LBB0_993
	s_barrier

.LBB0_1086:
	ds_read_b128 v[146:149], v155
	ds_read_b128 v[160:163], v155 offset:1024
	ds_read_b128 v[164:167], v155 offset:2048
	ds_read_b128 v[168:171], v155 offset:3072
	ds_read_b128 v[172:175], v156
	ds_read_b128 v[176:179], v156 offset:1024
	ds_read_b128 v[180:183], v156 offset:2048
	ds_read_b128 v[184:187], v156 offset:3072
	s_add_u32 s23, s54, 0xfffc0080
	s_addc_u32 s33, s55, -1
	s_cmp_eq_u32 s82, 12
	s_cselect_b32 s59, s20, s33
	s_cselect_b32 s58, s21, s23
	s_cselect_b32 s57, s47, s81
	s_cselect_b32 s56, s49, s80
	v_lshl_add_u64 v[150:151], s[54:55], 0, v[138:139]
	s_add_i32 m0, s64, 0xc000
	ds_read_b128 v[188:191], v157
	ds_read_b128 v[192:195], v157 offset:1024
	ds_read_b128 v[196:199], v157 offset:2048
	ds_read_b128 v[200:203], v157 offset:3072
	ds_read_b128 v[204:207], v157 offset:4096
	ds_read_b128 v[208:211], v157 offset:5120
	ds_read_b128 v[212:215], v157 offset:6144
	ds_read_b128 v[216:219], v157 offset:7168
	global_load_lds_dwordx4 v[150:151], off
	v_lshl_add_u64 v[150:151], s[54:55], 0, v[140:141]
	s_add_i32 m0, s64, 0xe000
	s_nop 0
	global_load_lds_dwordx4 v[150:151], off
	s_waitcnt vmcnt(8)
	s_waitcnt lgkmcnt(0)
	s_barrier
	v_mfma_f32_16x16x32_bf16 v[124:127], v[146:149], v[188:191], v[124:127]
	v_mfma_f32_16x16x32_bf16 v[120:123], v[164:167], v[188:191], v[120:123]
	v_mfma_f32_16x16x32_bf16 v[108:111], v[146:149], v[196:199], v[108:111]
	v_mfma_f32_16x16x32_bf16 v[104:107], v[164:167], v[196:199], v[104:107]
	v_mfma_f32_16x16x32_bf16 v[92:95], v[146:149], v[204:207], v[92:95]
	v_mfma_f32_16x16x32_bf16 v[88:91], v[164:167], v[204:207], v[88:91]
	v_mfma_f32_16x16x32_bf16 v[76:79], v[146:149], v[212:215], v[76:79]
	v_mfma_f32_16x16x32_bf16 v[72:75], v[164:167], v[212:215], v[72:75]
	v_mfma_f32_16x16x32_bf16 v[124:127], v[160:163], v[192:195], v[124:127]
	v_mfma_f32_16x16x32_bf16 v[120:123], v[168:171], v[192:195], v[120:123]
	v_mfma_f32_16x16x32_bf16 v[108:111], v[160:163], v[200:203], v[108:111]
	v_mfma_f32_16x16x32_bf16 v[104:107], v[168:171], v[200:203], v[104:107]
	v_mfma_f32_16x16x32_bf16 v[92:95], v[160:163], v[208:211], v[92:95]
	v_mfma_f32_16x16x32_bf16 v[88:91], v[168:171], v[208:211], v[88:91]
	v_mfma_f32_16x16x32_bf16 v[76:79], v[160:163], v[216:219], v[76:79]
	v_mfma_f32_16x16x32_bf16 v[72:75], v[168:171], v[216:219], v[72:75]
	v_mfma_f32_16x16x32_bf16 v[116:119], v[172:175], v[188:191], v[116:119]
	v_mfma_f32_16x16x32_bf16 v[112:115], v[180:183], v[188:191], v[112:115]
	v_mfma_f32_16x16x32_bf16 v[100:103], v[172:175], v[196:199], v[100:103]
	v_mfma_f32_16x16x32_bf16 v[96:99], v[180:183], v[196:199], v[96:99]
	v_mfma_f32_16x16x32_bf16 v[84:87], v[172:175], v[204:207], v[84:87]
	v_mfma_f32_16x16x32_bf16 v[80:83], v[180:183], v[204:207], v[80:83]
	v_mfma_f32_16x16x32_bf16 v[68:71], v[172:175], v[212:215], v[68:71]
	v_mfma_f32_16x16x32_bf16 v[64:67], v[180:183], v[212:215], v[64:67]
	v_mfma_f32_16x16x32_bf16 v[116:119], v[176:179], v[192:195], v[116:119]
	v_mfma_f32_16x16x32_bf16 v[112:115], v[184:187], v[192:195], v[112:115]
	v_mfma_f32_16x16x32_bf16 v[100:103], v[176:179], v[200:203], v[100:103]
	v_mfma_f32_16x16x32_bf16 v[96:99], v[184:187], v[200:203], v[96:99]
	v_mfma_f32_16x16x32_bf16 v[84:87], v[176:179], v[208:211], v[84:87]
	v_mfma_f32_16x16x32_bf16 v[80:83], v[184:187], v[208:211], v[80:83]
	v_mfma_f32_16x16x32_bf16 v[68:71], v[176:179], v[216:219], v[68:71]
	v_mfma_f32_16x16x32_bf16 v[64:67], v[184:187], v[216:219], v[64:67]
	s_barrier
	s_add_i32 s23, s73, s62
	v_lshl_add_u64 v[150:151], s[56:57], 0, v[132:133]
	s_mov_b32 m0, s23
	ds_read_b128 v[188:191], v157 offset:16384
	ds_read_b128 v[192:195], v157 offset:17408
	ds_read_b128 v[196:199], v157 offset:18432
	ds_read_b128 v[200:203], v157 offset:19456
	ds_read_b128 v[204:207], v157 offset:20480
	ds_read_b128 v[208:211], v157 offset:21504
	ds_read_b128 v[212:215], v157 offset:22528
	ds_read_b128 v[216:219], v157 offset:23552
	global_load_lds_dwordx4 v[150:151], off
	s_add_i32 m0, s23, 0x2000
	s_add_u32 s84, s56, 0x40000
	v_lshl_add_u64 v[220:221], s[56:57], 0, v[136:137]
	s_addc_u32 s85, s57, 0
	s_add_i32 s23, s74, s62
	global_load_lds_dwordx4 v[220:221], off
	v_lshl_add_u64 v[222:223], s[84:85], 0, v[132:133]
	s_mov_b32 m0, s23
	v_lshl_add_u64 v[224:225], s[58:59], 0, v[134:135]
	global_load_lds_dwordx4 v[222:223], off
	v_lshl_add_u64 v[222:223], s[84:85], 0, v[136:137]
	s_add_i32 m0, s23, 0x2000
	s_nop 0
	global_load_lds_dwordx4 v[222:223], off
	v_lshl_add_u64 v[222:223], s[58:59], 0, v[130:131]
	s_mov_b32 m0, s64
	s_nop 0
	global_load_lds_dwordx4 v[222:223], off
	s_mov_b32 m0, s65
	s_nop 0
	global_load_lds_dwordx4 v[224:225], off
	s_waitcnt vmcnt(8)
	s_waitcnt lgkmcnt(0)
	s_barrier
	v_mfma_f32_16x16x32_bf16 v[60:63], v[146:149], v[188:191], v[60:63]
	v_mfma_f32_16x16x32_bf16 v[56:59], v[164:167], v[188:191], v[56:59]
	v_mfma_f32_16x16x32_bf16 v[44:47], v[146:149], v[196:199], v[44:47]
	v_mfma_f32_16x16x32_bf16 v[40:43], v[164:167], v[196:199], v[40:43]
	v_mfma_f32_16x16x32_bf16 v[28:31], v[146:149], v[204:207], v[28:31]
	v_mfma_f32_16x16x32_bf16 v[24:27], v[164:167], v[204:207], v[24:27]
	v_mfma_f32_16x16x32_bf16 v[12:15], v[146:149], v[212:215], v[12:15]
	v_mfma_f32_16x16x32_bf16 v[8:11], v[164:167], v[212:215], v[8:11]
	v_mfma_f32_16x16x32_bf16 v[60:63], v[160:163], v[192:195], v[60:63]
	v_mfma_f32_16x16x32_bf16 v[56:59], v[168:171], v[192:195], v[56:59]
	v_mfma_f32_16x16x32_bf16 v[44:47], v[160:163], v[200:203], v[44:47]
	v_mfma_f32_16x16x32_bf16 v[40:43], v[168:171], v[200:203], v[40:43]
	v_mfma_f32_16x16x32_bf16 v[28:31], v[160:163], v[208:211], v[28:31]
	v_mfma_f32_16x16x32_bf16 v[24:27], v[168:171], v[208:211], v[24:27]
	v_mfma_f32_16x16x32_bf16 v[12:15], v[160:163], v[216:219], v[12:15]
	v_mfma_f32_16x16x32_bf16 v[8:11], v[168:171], v[216:219], v[8:11]
	v_mfma_f32_16x16x32_bf16 v[52:55], v[172:175], v[188:191], v[52:55]
	v_mfma_f32_16x16x32_bf16 v[48:51], v[180:183], v[188:191], v[48:51]
	v_mfma_f32_16x16x32_bf16 v[36:39], v[172:175], v[196:199], v[36:39]
	v_mfma_f32_16x16x32_bf16 v[32:35], v[180:183], v[196:199], v[32:35]
	v_mfma_f32_16x16x32_bf16 v[20:23], v[172:175], v[204:207], v[20:23]
	v_mfma_f32_16x16x32_bf16 v[16:19], v[180:183], v[204:207], v[16:19]
	v_mfma_f32_16x16x32_bf16 v[4:7], v[172:175], v[212:215], v[4:7]
	v_mfma_f32_16x16x32_bf16 v[0:3], v[180:183], v[212:215], v[0:3]
	v_mfma_f32_16x16x32_bf16 v[52:55], v[176:179], v[192:195], v[52:55]
	v_mfma_f32_16x16x32_bf16 v[48:51], v[184:187], v[192:195], v[48:51]
	v_mfma_f32_16x16x32_bf16 v[36:39], v[176:179], v[200:203], v[36:39]
	v_mfma_f32_16x16x32_bf16 v[32:35], v[184:187], v[200:203], v[32:35]
	v_mfma_f32_16x16x32_bf16 v[20:23], v[176:179], v[208:211], v[20:23]
	v_mfma_f32_16x16x32_bf16 v[16:19], v[184:187], v[208:211], v[16:19]
	v_mfma_f32_16x16x32_bf16 v[4:7], v[176:179], v[216:219], v[4:7]
	v_mfma_f32_16x16x32_bf16 v[0:3], v[184:187], v[216:219], v[0:3]
	s_barrier
	s_add_i32 s23, 0, 0x18000
	v_add_u32_e32 v159, s23, v153
	s_add_i32 s33, 0, 0x1c000
	ds_read_b128 v[146:149], v159
	ds_read_b128 v[160:163], v159 offset:1024
	ds_read_b128 v[164:167], v159 offset:2048
	ds_read_b128 v[168:171], v159 offset:3072
	v_add_u32_e32 v159, s33, v153
	ds_read_b128 v[172:175], v159
	ds_read_b128 v[176:179], v159 offset:1024
	ds_read_b128 v[180:183], v159 offset:2048
	ds_read_b128 v[184:187], v159 offset:3072
	s_add_u32 s58, s58, 0x40000
	s_addc_u32 s59, s59, 0
	s_mov_b32 m0, s66
	v_lshl_add_u64 v[226:227], s[58:59], 0, v[130:131]
	ds_read_b128 v[188:191], v157 offset:32768
	ds_read_b128 v[192:195], v157 offset:33792
	ds_read_b128 v[196:199], v157 offset:34816
	ds_read_b128 v[200:203], v157 offset:35840
	ds_read_b128 v[204:207], v157 offset:36864
	ds_read_b128 v[208:211], v157 offset:37888
	ds_read_b128 v[212:215], v157 offset:38912
	ds_read_b128 v[216:219], v157 offset:39936
	global_load_lds_dwordx4 v[226:227], off
	v_lshl_add_u64 v[226:227], s[58:59], 0, v[134:135]
	s_mov_b32 m0, s67
	s_nop 0
	global_load_lds_dwordx4 v[226:227], off
	s_waitcnt vmcnt(8)
	s_waitcnt lgkmcnt(0)
	s_barrier
	v_mfma_f32_16x16x32_bf16 v[124:127], v[146:149], v[188:191], v[124:127]
	v_mfma_f32_16x16x32_bf16 v[120:123], v[164:167], v[188:191], v[120:123]
	v_mfma_f32_16x16x32_bf16 v[108:111], v[146:149], v[196:199], v[108:111]
	v_mfma_f32_16x16x32_bf16 v[104:107], v[164:167], v[196:199], v[104:107]
	v_mfma_f32_16x16x32_bf16 v[92:95], v[146:149], v[204:207], v[92:95]
	v_mfma_f32_16x16x32_bf16 v[88:91], v[164:167], v[204:207], v[88:91]
	v_mfma_f32_16x16x32_bf16 v[76:79], v[146:149], v[212:215], v[76:79]
	v_mfma_f32_16x16x32_bf16 v[72:75], v[164:167], v[212:215], v[72:75]
	v_mfma_f32_16x16x32_bf16 v[124:127], v[160:163], v[192:195], v[124:127]
	v_mfma_f32_16x16x32_bf16 v[120:123], v[168:171], v[192:195], v[120:123]
	v_mfma_f32_16x16x32_bf16 v[108:111], v[160:163], v[200:203], v[108:111]
	v_mfma_f32_16x16x32_bf16 v[104:107], v[168:171], v[200:203], v[104:107]
	v_mfma_f32_16x16x32_bf16 v[92:95], v[160:163], v[208:211], v[92:95]
	v_mfma_f32_16x16x32_bf16 v[88:91], v[168:171], v[208:211], v[88:91]
	v_mfma_f32_16x16x32_bf16 v[76:79], v[160:163], v[216:219], v[76:79]
	v_mfma_f32_16x16x32_bf16 v[72:75], v[168:171], v[216:219], v[72:75]
	v_mfma_f32_16x16x32_bf16 v[116:119], v[172:175], v[188:191], v[116:119]
	v_mfma_f32_16x16x32_bf16 v[112:115], v[180:183], v[188:191], v[112:115]
	v_mfma_f32_16x16x32_bf16 v[100:103], v[172:175], v[196:199], v[100:103]
	v_mfma_f32_16x16x32_bf16 v[96:99], v[180:183], v[196:199], v[96:99]
	v_mfma_f32_16x16x32_bf16 v[84:87], v[172:175], v[204:207], v[84:87]
	v_mfma_f32_16x16x32_bf16 v[80:83], v[180:183], v[204:207], v[80:83]
	v_mfma_f32_16x16x32_bf16 v[68:71], v[172:175], v[212:215], v[68:71]
	v_mfma_f32_16x16x32_bf16 v[64:67], v[180:183], v[212:215], v[64:67]
	v_mfma_f32_16x16x32_bf16 v[116:119], v[176:179], v[192:195], v[116:119]
	v_mfma_f32_16x16x32_bf16 v[112:115], v[184:187], v[192:195], v[112:115]
	v_mfma_f32_16x16x32_bf16 v[100:103], v[176:179], v[200:203], v[100:103]
	v_mfma_f32_16x16x32_bf16 v[96:99], v[184:187], v[200:203], v[96:99]
	v_mfma_f32_16x16x32_bf16 v[84:87], v[176:179], v[208:211], v[84:87]
	v_mfma_f32_16x16x32_bf16 v[80:83], v[184:187], v[208:211], v[80:83]
	v_mfma_f32_16x16x32_bf16 v[68:71], v[176:179], v[216:219], v[68:71]
	v_mfma_f32_16x16x32_bf16 v[64:67], v[184:187], v[216:219], v[64:67]
	s_barrier
	s_add_i32 s23, s23, s62
	v_lshl_add_u64 v[150:151], v[150:151], 0, s[16:17]
	s_mov_b32 m0, s23
	ds_read_b128 v[188:191], v157 offset:49152
	ds_read_b128 v[192:195], v157 offset:50176
	ds_read_b128 v[196:199], v157 offset:51200
	ds_read_b128 v[200:203], v157 offset:52224
	ds_read_b128 v[204:207], v157 offset:53248
	ds_read_b128 v[208:211], v157 offset:54272
	ds_read_b128 v[212:215], v157 offset:55296
	ds_read_b128 v[216:219], v157 offset:56320
	global_load_lds_dwordx4 v[150:151], off
	s_add_i32 m0, s23, 0x2000
	s_add_u32 s56, s56, 0x40080
	v_lshl_add_u64 v[150:151], v[220:221], 0, s[16:17]
	s_addc_u32 s57, s57, 0
	s_add_i32 s23, s33, s62
	global_load_lds_dwordx4 v[150:151], off
	v_lshl_add_u64 v[150:151], s[56:57], 0, v[132:133]
	s_mov_b32 m0, s23
	s_nop 0
	global_load_lds_dwordx4 v[150:151], off
	v_lshl_add_u64 v[150:151], s[56:57], 0, v[136:137]
	s_add_i32 m0, s23, 0x2000
	s_nop 0
	global_load_lds_dwordx4 v[150:151], off
	v_lshl_add_u64 v[150:151], v[222:223], 0, s[16:17]
	s_mov_b32 m0, s70
	s_nop 0
	global_load_lds_dwordx4 v[150:151], off
	v_lshl_add_u64 v[150:151], v[224:225], 0, s[16:17]
	s_mov_b32 m0, s71
	s_nop 0
	global_load_lds_dwordx4 v[150:151], off
	s_waitcnt vmcnt(8)
	s_waitcnt lgkmcnt(0)
	s_barrier
	v_mfma_f32_16x16x32_bf16 v[60:63], v[146:149], v[188:191], v[60:63]
	v_mfma_f32_16x16x32_bf16 v[56:59], v[164:167], v[188:191], v[56:59]
	v_mfma_f32_16x16x32_bf16 v[44:47], v[146:149], v[196:199], v[44:47]
	v_mfma_f32_16x16x32_bf16 v[40:43], v[164:167], v[196:199], v[40:43]
	v_mfma_f32_16x16x32_bf16 v[28:31], v[146:149], v[204:207], v[28:31]
	v_mfma_f32_16x16x32_bf16 v[24:27], v[164:167], v[204:207], v[24:27]
	v_mfma_f32_16x16x32_bf16 v[12:15], v[146:149], v[212:215], v[12:15]
	v_mfma_f32_16x16x32_bf16 v[8:11], v[164:167], v[212:215], v[8:11]
	v_mfma_f32_16x16x32_bf16 v[60:63], v[160:163], v[192:195], v[60:63]
	v_mfma_f32_16x16x32_bf16 v[56:59], v[168:171], v[192:195], v[56:59]
	v_mfma_f32_16x16x32_bf16 v[44:47], v[160:163], v[200:203], v[44:47]
	v_mfma_f32_16x16x32_bf16 v[40:43], v[168:171], v[200:203], v[40:43]
	v_mfma_f32_16x16x32_bf16 v[28:31], v[160:163], v[208:211], v[28:31]
	v_mfma_f32_16x16x32_bf16 v[24:27], v[168:171], v[208:211], v[24:27]
	v_mfma_f32_16x16x32_bf16 v[12:15], v[160:163], v[216:219], v[12:15]
	v_mfma_f32_16x16x32_bf16 v[8:11], v[168:171], v[216:219], v[8:11]
	v_mfma_f32_16x16x32_bf16 v[52:55], v[172:175], v[188:191], v[52:55]
	v_mfma_f32_16x16x32_bf16 v[48:51], v[180:183], v[188:191], v[48:51]
	v_mfma_f32_16x16x32_bf16 v[36:39], v[172:175], v[196:199], v[36:39]
	v_mfma_f32_16x16x32_bf16 v[32:35], v[180:183], v[196:199], v[32:35]
	v_mfma_f32_16x16x32_bf16 v[20:23], v[172:175], v[204:207], v[20:23]
	v_mfma_f32_16x16x32_bf16 v[16:19], v[180:183], v[204:207], v[16:19]
	v_mfma_f32_16x16x32_bf16 v[4:7], v[172:175], v[212:215], v[4:7]
	v_mfma_f32_16x16x32_bf16 v[0:3], v[180:183], v[212:215], v[0:3]
	v_mfma_f32_16x16x32_bf16 v[52:55], v[176:179], v[192:195], v[52:55]
	v_mfma_f32_16x16x32_bf16 v[48:51], v[184:187], v[192:195], v[48:51]
	v_mfma_f32_16x16x32_bf16 v[36:39], v[176:179], v[200:203], v[36:39]
	v_mfma_f32_16x16x32_bf16 v[32:35], v[184:187], v[200:203], v[32:35]
	v_mfma_f32_16x16x32_bf16 v[20:23], v[176:179], v[208:211], v[20:23]
	v_mfma_f32_16x16x32_bf16 v[16:19], v[184:187], v[208:211], v[16:19]
	v_mfma_f32_16x16x32_bf16 v[4:7], v[176:179], v[216:219], v[4:7]
	v_mfma_f32_16x16x32_bf16 v[0:3], v[184:187], v[216:219], v[0:3]
	s_barrier
	s_add_i32 s82, s82, 2
	s_add_u32 s54, s54, 0x100
	s_addc_u32 s55, s55, 0
	s_add_u32 s80, s80, 0x100
	s_addc_u32 s81, s81, 0
	s_cmp_gt_u32 s82, 13
	s_cbranch_scc0 .LBB0_1086
	s_and_b64 vcc, exec, s[18:19]
	s_cbranch_vccz .LBB0_1089
	s_barrier

.LBB0_1246:
	ds_read_b128 v[146:149], v155
	ds_read_b128 v[160:163], v155 offset:1024
	ds_read_b128 v[164:167], v155 offset:2048
	ds_read_b128 v[168:171], v155 offset:3072
	ds_read_b128 v[172:175], v156
	ds_read_b128 v[176:179], v156 offset:1024
	ds_read_b128 v[180:183], v156 offset:2048
	ds_read_b128 v[184:187], v156 offset:3072
	s_add_u32 s23, s46, 0xfffc0080
	s_addc_u32 s33, s47, -1
	s_cmp_eq_u32 s67, 12
	s_cselect_b32 s51, s20, s33
	s_cselect_b32 s50, s21, s23
	s_cselect_b32 s49, s19, s66
	s_cselect_b32 s48, s37, s65
	v_lshl_add_u64 v[220:221], s[46:47], 0, v[138:139]
	s_add_i32 m0, s43, 0xc000
	ds_read_b128 v[188:191], v157
	ds_read_b128 v[192:195], v157 offset:1024
	ds_read_b128 v[196:199], v157 offset:2048
	ds_read_b128 v[200:203], v157 offset:3072
	ds_read_b128 v[204:207], v157 offset:4096
	ds_read_b128 v[208:211], v157 offset:5120
	ds_read_b128 v[212:215], v157 offset:6144
	ds_read_b128 v[216:219], v157 offset:7168
	global_load_lds_dwordx4 v[220:221], off
	v_lshl_add_u64 v[220:221], s[46:47], 0, v[140:141]
	s_add_i32 m0, s43, 0xe000
	s_nop 0
	global_load_lds_dwordx4 v[220:221], off
	s_waitcnt vmcnt(8)
	s_waitcnt lgkmcnt(0)
	s_barrier
	v_mfma_f32_16x16x32_bf16 v[124:127], v[146:149], v[188:191], v[124:127]
	v_mfma_f32_16x16x32_bf16 v[120:123], v[164:167], v[188:191], v[120:123]
	v_mfma_f32_16x16x32_bf16 v[108:111], v[146:149], v[196:199], v[108:111]
	v_mfma_f32_16x16x32_bf16 v[104:107], v[164:167], v[196:199], v[104:107]
	v_mfma_f32_16x16x32_bf16 v[92:95], v[146:149], v[204:207], v[92:95]
	v_mfma_f32_16x16x32_bf16 v[88:91], v[164:167], v[204:207], v[88:91]
	v_mfma_f32_16x16x32_bf16 v[76:79], v[146:149], v[212:215], v[76:79]
	v_mfma_f32_16x16x32_bf16 v[72:75], v[164:167], v[212:215], v[72:75]
	v_mfma_f32_16x16x32_bf16 v[124:127], v[160:163], v[192:195], v[124:127]
	v_mfma_f32_16x16x32_bf16 v[120:123], v[168:171], v[192:195], v[120:123]
	v_mfma_f32_16x16x32_bf16 v[108:111], v[160:163], v[200:203], v[108:111]
	v_mfma_f32_16x16x32_bf16 v[104:107], v[168:171], v[200:203], v[104:107]
	v_mfma_f32_16x16x32_bf16 v[92:95], v[160:163], v[208:211], v[92:95]
	v_mfma_f32_16x16x32_bf16 v[88:91], v[168:171], v[208:211], v[88:91]
	v_mfma_f32_16x16x32_bf16 v[76:79], v[160:163], v[216:219], v[76:79]
	v_mfma_f32_16x16x32_bf16 v[72:75], v[168:171], v[216:219], v[72:75]
	v_mfma_f32_16x16x32_bf16 v[116:119], v[172:175], v[188:191], v[116:119]
	v_mfma_f32_16x16x32_bf16 v[112:115], v[180:183], v[188:191], v[112:115]
	v_mfma_f32_16x16x32_bf16 v[100:103], v[172:175], v[196:199], v[100:103]
	v_mfma_f32_16x16x32_bf16 v[96:99], v[180:183], v[196:199], v[96:99]
	v_mfma_f32_16x16x32_bf16 v[84:87], v[172:175], v[204:207], v[84:87]
	v_mfma_f32_16x16x32_bf16 v[80:83], v[180:183], v[204:207], v[80:83]
	v_mfma_f32_16x16x32_bf16 v[68:71], v[172:175], v[212:215], v[68:71]
	v_mfma_f32_16x16x32_bf16 v[64:67], v[180:183], v[212:215], v[64:67]
	v_mfma_f32_16x16x32_bf16 v[116:119], v[176:179], v[192:195], v[116:119]
	v_mfma_f32_16x16x32_bf16 v[112:115], v[184:187], v[192:195], v[112:115]
	v_mfma_f32_16x16x32_bf16 v[100:103], v[176:179], v[200:203], v[100:103]
	v_mfma_f32_16x16x32_bf16 v[96:99], v[184:187], v[200:203], v[96:99]
	v_mfma_f32_16x16x32_bf16 v[84:87], v[176:179], v[208:211], v[84:87]
	v_mfma_f32_16x16x32_bf16 v[80:83], v[184:187], v[208:211], v[80:83]
	v_mfma_f32_16x16x32_bf16 v[68:71], v[176:179], v[216:219], v[68:71]
	v_mfma_f32_16x16x32_bf16 v[64:67], v[184:187], v[216:219], v[64:67]
	s_barrier
	s_add_i32 s23, s63, s54
	v_lshl_add_u64 v[220:221], s[48:49], 0, v[132:133]
	s_mov_b32 m0, s23
	ds_read_b128 v[188:191], v157 offset:16384
	ds_read_b128 v[192:195], v157 offset:17408
	ds_read_b128 v[196:199], v157 offset:18432
	ds_read_b128 v[200:203], v157 offset:19456
	ds_read_b128 v[204:207], v157 offset:20480
	ds_read_b128 v[208:211], v157 offset:21504
	ds_read_b128 v[212:215], v157 offset:22528
	ds_read_b128 v[216:219], v157 offset:23552
	global_load_lds_dwordx4 v[220:221], off
	s_add_i32 m0, s23, 0x2000
	s_add_u32 s68, s48, 0x40000
	v_lshl_add_u64 v[222:223], s[48:49], 0, v[136:137]
	s_addc_u32 s69, s49, 0
	s_add_i32 s23, s64, s54
	global_load_lds_dwordx4 v[222:223], off
	v_lshl_add_u64 v[224:225], s[68:69], 0, v[132:133]
	s_mov_b32 m0, s23
	v_lshl_add_u64 v[226:227], s[50:51], 0, v[134:135]
	global_load_lds_dwordx4 v[224:225], off
	v_lshl_add_u64 v[224:225], s[68:69], 0, v[136:137]
	s_add_i32 m0, s23, 0x2000
	s_nop 0
	global_load_lds_dwordx4 v[224:225], off
	v_lshl_add_u64 v[224:225], s[50:51], 0, v[130:131]
	s_mov_b32 m0, s43
	s_nop 0
	global_load_lds_dwordx4 v[224:225], off
	s_mov_b32 m0, s45
	s_nop 0
	global_load_lds_dwordx4 v[226:227], off
	s_waitcnt vmcnt(8)
	s_waitcnt lgkmcnt(0)
	s_barrier
	v_mfma_f32_16x16x32_bf16 v[60:63], v[146:149], v[188:191], v[60:63]
	v_mfma_f32_16x16x32_bf16 v[56:59], v[164:167], v[188:191], v[56:59]
	v_mfma_f32_16x16x32_bf16 v[44:47], v[146:149], v[196:199], v[44:47]
	v_mfma_f32_16x16x32_bf16 v[40:43], v[164:167], v[196:199], v[40:43]
	v_mfma_f32_16x16x32_bf16 v[28:31], v[146:149], v[204:207], v[28:31]
	v_mfma_f32_16x16x32_bf16 v[24:27], v[164:167], v[204:207], v[24:27]
	v_mfma_f32_16x16x32_bf16 v[12:15], v[146:149], v[212:215], v[12:15]
	v_mfma_f32_16x16x32_bf16 v[8:11], v[164:167], v[212:215], v[8:11]
	v_mfma_f32_16x16x32_bf16 v[60:63], v[160:163], v[192:195], v[60:63]
	v_mfma_f32_16x16x32_bf16 v[56:59], v[168:171], v[192:195], v[56:59]
	v_mfma_f32_16x16x32_bf16 v[44:47], v[160:163], v[200:203], v[44:47]
	v_mfma_f32_16x16x32_bf16 v[40:43], v[168:171], v[200:203], v[40:43]
	v_mfma_f32_16x16x32_bf16 v[28:31], v[160:163], v[208:211], v[28:31]
	v_mfma_f32_16x16x32_bf16 v[24:27], v[168:171], v[208:211], v[24:27]
	v_mfma_f32_16x16x32_bf16 v[12:15], v[160:163], v[216:219], v[12:15]
	v_mfma_f32_16x16x32_bf16 v[8:11], v[168:171], v[216:219], v[8:11]
	v_mfma_f32_16x16x32_bf16 v[52:55], v[172:175], v[188:191], v[52:55]
	v_mfma_f32_16x16x32_bf16 v[48:51], v[180:183], v[188:191], v[48:51]
	v_mfma_f32_16x16x32_bf16 v[36:39], v[172:175], v[196:199], v[36:39]
	v_mfma_f32_16x16x32_bf16 v[32:35], v[180:183], v[196:199], v[32:35]
	v_mfma_f32_16x16x32_bf16 v[20:23], v[172:175], v[204:207], v[20:23]
	v_mfma_f32_16x16x32_bf16 v[16:19], v[180:183], v[204:207], v[16:19]
	v_mfma_f32_16x16x32_bf16 v[4:7], v[172:175], v[212:215], v[4:7]
	v_mfma_f32_16x16x32_bf16 v[0:3], v[180:183], v[212:215], v[0:3]
	v_mfma_f32_16x16x32_bf16 v[52:55], v[176:179], v[192:195], v[52:55]
	v_mfma_f32_16x16x32_bf16 v[48:51], v[184:187], v[192:195], v[48:51]
	v_mfma_f32_16x16x32_bf16 v[36:39], v[176:179], v[200:203], v[36:39]
	v_mfma_f32_16x16x32_bf16 v[32:35], v[184:187], v[200:203], v[32:35]
	v_mfma_f32_16x16x32_bf16 v[20:23], v[176:179], v[208:211], v[20:23]
	v_mfma_f32_16x16x32_bf16 v[16:19], v[184:187], v[208:211], v[16:19]
	v_mfma_f32_16x16x32_bf16 v[4:7], v[176:179], v[216:219], v[4:7]
	v_mfma_f32_16x16x32_bf16 v[0:3], v[184:187], v[216:219], v[0:3]
	s_barrier
	s_add_i32 s23, 0, 0x18000
	v_add_u32_e32 v159, s23, v153
	s_add_i32 s33, 0, 0x1c000
	ds_read_b128 v[146:149], v159
	ds_read_b128 v[160:163], v159 offset:1024
	ds_read_b128 v[164:167], v159 offset:2048
	ds_read_b128 v[168:171], v159 offset:3072
	v_add_u32_e32 v159, s33, v153
	ds_read_b128 v[172:175], v159
	ds_read_b128 v[176:179], v159 offset:1024
	ds_read_b128 v[180:183], v159 offset:2048
	ds_read_b128 v[184:187], v159 offset:3072
	s_add_u32 s50, s50, 0x40000
	s_addc_u32 s51, s51, 0
	s_mov_b32 m0, s55
	v_lshl_add_u64 v[228:229], s[50:51], 0, v[130:131]
	ds_read_b128 v[188:191], v157 offset:32768
	ds_read_b128 v[192:195], v157 offset:33792
	ds_read_b128 v[196:199], v157 offset:34816
	ds_read_b128 v[200:203], v157 offset:35840
	ds_read_b128 v[204:207], v157 offset:36864
	ds_read_b128 v[208:211], v157 offset:37888
	ds_read_b128 v[212:215], v157 offset:38912
	ds_read_b128 v[216:219], v157 offset:39936
	global_load_lds_dwordx4 v[228:229], off
	v_lshl_add_u64 v[228:229], s[50:51], 0, v[134:135]
	s_mov_b32 m0, s56
	s_nop 0
	global_load_lds_dwordx4 v[228:229], off
	s_waitcnt vmcnt(8)
	s_waitcnt lgkmcnt(0)
	s_barrier
	v_mfma_f32_16x16x32_bf16 v[124:127], v[146:149], v[188:191], v[124:127]
	v_mfma_f32_16x16x32_bf16 v[120:123], v[164:167], v[188:191], v[120:123]
	v_mfma_f32_16x16x32_bf16 v[108:111], v[146:149], v[196:199], v[108:111]
	v_mfma_f32_16x16x32_bf16 v[104:107], v[164:167], v[196:199], v[104:107]
	v_mfma_f32_16x16x32_bf16 v[92:95], v[146:149], v[204:207], v[92:95]
	v_mfma_f32_16x16x32_bf16 v[88:91], v[164:167], v[204:207], v[88:91]
	v_mfma_f32_16x16x32_bf16 v[76:79], v[146:149], v[212:215], v[76:79]
	v_mfma_f32_16x16x32_bf16 v[72:75], v[164:167], v[212:215], v[72:75]
	v_mfma_f32_16x16x32_bf16 v[124:127], v[160:163], v[192:195], v[124:127]
	v_mfma_f32_16x16x32_bf16 v[120:123], v[168:171], v[192:195], v[120:123]
	v_mfma_f32_16x16x32_bf16 v[108:111], v[160:163], v[200:203], v[108:111]
	v_mfma_f32_16x16x32_bf16 v[104:107], v[168:171], v[200:203], v[104:107]
	v_mfma_f32_16x16x32_bf16 v[92:95], v[160:163], v[208:211], v[92:95]
	v_mfma_f32_16x16x32_bf16 v[88:91], v[168:171], v[208:211], v[88:91]
	v_mfma_f32_16x16x32_bf16 v[76:79], v[160:163], v[216:219], v[76:79]
	v_mfma_f32_16x16x32_bf16 v[72:75], v[168:171], v[216:219], v[72:75]
	v_mfma_f32_16x16x32_bf16 v[116:119], v[172:175], v[188:191], v[116:119]
	v_mfma_f32_16x16x32_bf16 v[112:115], v[180:183], v[188:191], v[112:115]
	v_mfma_f32_16x16x32_bf16 v[100:103], v[172:175], v[196:199], v[100:103]
	v_mfma_f32_16x16x32_bf16 v[96:99], v[180:183], v[196:199], v[96:99]
	v_mfma_f32_16x16x32_bf16 v[84:87], v[172:175], v[204:207], v[84:87]
	v_mfma_f32_16x16x32_bf16 v[80:83], v[180:183], v[204:207], v[80:83]
	v_mfma_f32_16x16x32_bf16 v[68:71], v[172:175], v[212:215], v[68:71]
	v_mfma_f32_16x16x32_bf16 v[64:67], v[180:183], v[212:215], v[64:67]
	v_mfma_f32_16x16x32_bf16 v[116:119], v[176:179], v[192:195], v[116:119]
	v_mfma_f32_16x16x32_bf16 v[112:115], v[184:187], v[192:195], v[112:115]
	v_mfma_f32_16x16x32_bf16 v[100:103], v[176:179], v[200:203], v[100:103]
	v_mfma_f32_16x16x32_bf16 v[96:99], v[184:187], v[200:203], v[96:99]
	v_mfma_f32_16x16x32_bf16 v[84:87], v[176:179], v[208:211], v[84:87]
	v_mfma_f32_16x16x32_bf16 v[80:83], v[184:187], v[208:211], v[80:83]
	v_mfma_f32_16x16x32_bf16 v[68:71], v[176:179], v[216:219], v[68:71]
	v_mfma_f32_16x16x32_bf16 v[64:67], v[184:187], v[216:219], v[64:67]
	s_barrier
	s_add_i32 s23, s23, s54
	v_lshl_add_u64 v[220:221], v[220:221], 0, s[14:15]
	s_mov_b32 m0, s23
	ds_read_b128 v[188:191], v157 offset:49152
	ds_read_b128 v[192:195], v157 offset:50176
	ds_read_b128 v[196:199], v157 offset:51200
	ds_read_b128 v[200:203], v157 offset:52224
	ds_read_b128 v[204:207], v157 offset:53248
	ds_read_b128 v[208:211], v157 offset:54272
	ds_read_b128 v[212:215], v157 offset:55296
	ds_read_b128 v[216:219], v157 offset:56320
	global_load_lds_dwordx4 v[220:221], off
	s_add_i32 m0, s23, 0x2000
	s_add_u32 s48, s48, 0x40080
	v_lshl_add_u64 v[220:221], v[222:223], 0, s[14:15]
	s_addc_u32 s49, s49, 0
	s_add_i32 s23, s33, s54
	global_load_lds_dwordx4 v[220:221], off
	v_lshl_add_u64 v[220:221], s[48:49], 0, v[132:133]
	s_mov_b32 m0, s23
	s_nop 0
	global_load_lds_dwordx4 v[220:221], off
	v_lshl_add_u64 v[220:221], s[48:49], 0, v[136:137]
	s_add_i32 m0, s23, 0x2000
	s_nop 0
	global_load_lds_dwordx4 v[220:221], off
	v_lshl_add_u64 v[220:221], v[224:225], 0, s[14:15]
	s_mov_b32 m0, s60
	s_nop 0
	global_load_lds_dwordx4 v[220:221], off
	v_lshl_add_u64 v[220:221], v[226:227], 0, s[14:15]
	s_mov_b32 m0, s61
	s_nop 0
	global_load_lds_dwordx4 v[220:221], off
	s_waitcnt vmcnt(8)
	s_waitcnt lgkmcnt(0)
	s_barrier
	v_mfma_f32_16x16x32_bf16 v[60:63], v[146:149], v[188:191], v[60:63]
	v_mfma_f32_16x16x32_bf16 v[56:59], v[164:167], v[188:191], v[56:59]
	v_mfma_f32_16x16x32_bf16 v[44:47], v[146:149], v[196:199], v[44:47]
	v_mfma_f32_16x16x32_bf16 v[40:43], v[164:167], v[196:199], v[40:43]
	v_mfma_f32_16x16x32_bf16 v[28:31], v[146:149], v[204:207], v[28:31]
	v_mfma_f32_16x16x32_bf16 v[24:27], v[164:167], v[204:207], v[24:27]
	v_mfma_f32_16x16x32_bf16 v[12:15], v[146:149], v[212:215], v[12:15]
	v_mfma_f32_16x16x32_bf16 v[8:11], v[164:167], v[212:215], v[8:11]
	v_mfma_f32_16x16x32_bf16 v[60:63], v[160:163], v[192:195], v[60:63]
	v_mfma_f32_16x16x32_bf16 v[56:59], v[168:171], v[192:195], v[56:59]
	v_mfma_f32_16x16x32_bf16 v[44:47], v[160:163], v[200:203], v[44:47]
	v_mfma_f32_16x16x32_bf16 v[40:43], v[168:171], v[200:203], v[40:43]
	v_mfma_f32_16x16x32_bf16 v[28:31], v[160:163], v[208:211], v[28:31]
	v_mfma_f32_16x16x32_bf16 v[24:27], v[168:171], v[208:211], v[24:27]
	v_mfma_f32_16x16x32_bf16 v[12:15], v[160:163], v[216:219], v[12:15]
	v_mfma_f32_16x16x32_bf16 v[8:11], v[168:171], v[216:219], v[8:11]
	v_mfma_f32_16x16x32_bf16 v[52:55], v[172:175], v[188:191], v[52:55]
	v_mfma_f32_16x16x32_bf16 v[48:51], v[180:183], v[188:191], v[48:51]
	v_mfma_f32_16x16x32_bf16 v[36:39], v[172:175], v[196:199], v[36:39]
	v_mfma_f32_16x16x32_bf16 v[32:35], v[180:183], v[196:199], v[32:35]
	v_mfma_f32_16x16x32_bf16 v[20:23], v[172:175], v[204:207], v[20:23]
	v_mfma_f32_16x16x32_bf16 v[16:19], v[180:183], v[204:207], v[16:19]
	v_mfma_f32_16x16x32_bf16 v[4:7], v[172:175], v[212:215], v[4:7]
	v_mfma_f32_16x16x32_bf16 v[0:3], v[180:183], v[212:215], v[0:3]
	v_mfma_f32_16x16x32_bf16 v[52:55], v[176:179], v[192:195], v[52:55]
	v_mfma_f32_16x16x32_bf16 v[48:51], v[184:187], v[192:195], v[48:51]
	v_mfma_f32_16x16x32_bf16 v[36:39], v[176:179], v[200:203], v[36:39]
	v_mfma_f32_16x16x32_bf16 v[32:35], v[184:187], v[200:203], v[32:35]
	v_mfma_f32_16x16x32_bf16 v[20:23], v[176:179], v[208:211], v[20:23]
	v_mfma_f32_16x16x32_bf16 v[16:19], v[184:187], v[208:211], v[16:19]
	v_mfma_f32_16x16x32_bf16 v[4:7], v[176:179], v[216:219], v[4:7]
	v_mfma_f32_16x16x32_bf16 v[0:3], v[184:187], v[216:219], v[0:3]
	s_barrier
	s_add_i32 s67, s67, 2
	s_add_u32 s46, s46, 0x100
	s_addc_u32 s47, s47, 0
	s_add_u32 s65, s65, 0x100
	s_addc_u32 s66, s66, 0
	s_cmp_gt_u32 s67, 13
	s_cbranch_scc0 .LBB0_1246
	s_and_b64 vcc, exec, s[16:17]
	s_cbranch_vccz .LBB0_1249
	s_barrier

.LBB0_1342:
	ds_read_b128 v[146:149], v154
	ds_read_b128 v[158:161], v154 offset:1024
	ds_read_b128 v[162:165], v154 offset:2048
	ds_read_b128 v[166:169], v154 offset:3072
	ds_read_b128 v[170:173], v155
	ds_read_b128 v[174:177], v155 offset:1024
	ds_read_b128 v[178:181], v155 offset:2048
	ds_read_b128 v[182:185], v155 offset:3072
	s_add_u32 s23, s40, 0xfffc0080
	s_addc_u32 s33, s41, -1
	s_cmp_eq_u32 s67, 12
	s_cselect_b32 s45, s19, s33
	s_cselect_b32 s44, s20, s23
	s_cselect_b32 s43, s17, s66
	s_cselect_b32 s42, s21, s65
	v_lshl_add_u64 v[218:219], s[40:41], 0, v[138:139]
	s_add_i32 m0, s52, 0xc000
	ds_read_b128 v[186:189], v156
	ds_read_b128 v[190:193], v156 offset:1024
	ds_read_b128 v[194:197], v156 offset:2048
	ds_read_b128 v[198:201], v156 offset:3072
	ds_read_b128 v[202:205], v156 offset:4096
	ds_read_b128 v[206:209], v156 offset:5120
	ds_read_b128 v[210:213], v156 offset:6144
	ds_read_b128 v[214:217], v156 offset:7168
	global_load_lds_dwordx4 v[218:219], off
	v_lshl_add_u64 v[218:219], s[40:41], 0, v[140:141]
	s_add_i32 m0, s52, 0xe000
	s_nop 0
	global_load_lds_dwordx4 v[218:219], off
	s_waitcnt vmcnt(8)
	s_waitcnt lgkmcnt(0)
	s_barrier
	v_mfma_f32_16x16x32_bf16 v[116:119], v[146:149], v[186:189], v[116:119]
	v_mfma_f32_16x16x32_bf16 v[112:115], v[162:165], v[186:189], v[112:115]
	v_mfma_f32_16x16x32_bf16 v[100:103], v[146:149], v[194:197], v[100:103]
	v_mfma_f32_16x16x32_bf16 v[96:99], v[162:165], v[194:197], v[96:99]
	v_mfma_f32_16x16x32_bf16 v[84:87], v[146:149], v[202:205], v[84:87]
	v_mfma_f32_16x16x32_bf16 v[80:83], v[162:165], v[202:205], v[80:83]
	v_mfma_f32_16x16x32_bf16 v[72:75], v[146:149], v[210:213], v[72:75]
	v_mfma_f32_16x16x32_bf16 v[64:67], v[162:165], v[210:213], v[64:67]
	v_mfma_f32_16x16x32_bf16 v[116:119], v[158:161], v[190:193], v[116:119]
	v_mfma_f32_16x16x32_bf16 v[112:115], v[166:169], v[190:193], v[112:115]
	v_mfma_f32_16x16x32_bf16 v[100:103], v[158:161], v[198:201], v[100:103]
	v_mfma_f32_16x16x32_bf16 v[96:99], v[166:169], v[198:201], v[96:99]
	v_mfma_f32_16x16x32_bf16 v[84:87], v[158:161], v[206:209], v[84:87]
	v_mfma_f32_16x16x32_bf16 v[80:83], v[166:169], v[206:209], v[80:83]
	v_mfma_f32_16x16x32_bf16 v[72:75], v[158:161], v[214:217], v[72:75]
	v_mfma_f32_16x16x32_bf16 v[64:67], v[166:169], v[214:217], v[64:67]
	v_mfma_f32_16x16x32_bf16 v[124:127], v[170:173], v[186:189], v[124:127]
	v_mfma_f32_16x16x32_bf16 v[120:123], v[178:181], v[186:189], v[120:123]
	v_mfma_f32_16x16x32_bf16 v[108:111], v[170:173], v[194:197], v[108:111]
	v_mfma_f32_16x16x32_bf16 v[104:107], v[178:181], v[194:197], v[104:107]
	v_mfma_f32_16x16x32_bf16 v[92:95], v[170:173], v[202:205], v[92:95]
	v_mfma_f32_16x16x32_bf16 v[88:91], v[178:181], v[202:205], v[88:91]
	v_mfma_f32_16x16x32_bf16 v[76:79], v[170:173], v[210:213], v[76:79]
	v_mfma_f32_16x16x32_bf16 v[68:71], v[178:181], v[210:213], v[68:71]
	v_mfma_f32_16x16x32_bf16 v[124:127], v[174:177], v[190:193], v[124:127]
	v_mfma_f32_16x16x32_bf16 v[120:123], v[182:185], v[190:193], v[120:123]
	v_mfma_f32_16x16x32_bf16 v[108:111], v[174:177], v[198:201], v[108:111]
	v_mfma_f32_16x16x32_bf16 v[104:107], v[182:185], v[198:201], v[104:107]
	v_mfma_f32_16x16x32_bf16 v[92:95], v[174:177], v[206:209], v[92:95]
	v_mfma_f32_16x16x32_bf16 v[88:91], v[182:185], v[206:209], v[88:91]
	v_mfma_f32_16x16x32_bf16 v[76:79], v[174:177], v[214:217], v[76:79]
	v_mfma_f32_16x16x32_bf16 v[68:71], v[182:185], v[214:217], v[68:71]
	s_barrier
	s_add_i32 s23, s61, s50
	v_lshl_add_u64 v[218:219], s[42:43], 0, v[132:133]
	s_mov_b32 m0, s23
	ds_read_b128 v[186:189], v156 offset:16384
	ds_read_b128 v[190:193], v156 offset:17408
	ds_read_b128 v[194:197], v156 offset:18432
	ds_read_b128 v[198:201], v156 offset:19456
	ds_read_b128 v[202:205], v156 offset:20480
	ds_read_b128 v[206:209], v156 offset:21504
	ds_read_b128 v[210:213], v156 offset:22528
	ds_read_b128 v[214:217], v156 offset:23552
	global_load_lds_dwordx4 v[218:219], off
	s_add_i32 m0, s23, 0x2000
	s_add_u32 s68, s42, 0x40000
	v_lshl_add_u64 v[220:221], s[42:43], 0, v[136:137]
	s_addc_u32 s69, s43, 0
	s_add_i32 s23, s62, s50
	global_load_lds_dwordx4 v[220:221], off
	v_lshl_add_u64 v[222:223], s[68:69], 0, v[132:133]
	s_mov_b32 m0, s23
	v_lshl_add_u64 v[224:225], s[44:45], 0, v[134:135]
	global_load_lds_dwordx4 v[222:223], off
	v_lshl_add_u64 v[222:223], s[68:69], 0, v[136:137]
	s_add_i32 m0, s23, 0x2000
	s_nop 0
	global_load_lds_dwordx4 v[222:223], off
	v_lshl_add_u64 v[222:223], s[44:45], 0, v[130:131]
	s_mov_b32 m0, s52
	s_nop 0
	global_load_lds_dwordx4 v[222:223], off
	s_mov_b32 m0, s53
	s_nop 0
	global_load_lds_dwordx4 v[224:225], off
	s_waitcnt vmcnt(8)
	s_waitcnt lgkmcnt(0)
	s_barrier
	v_mfma_f32_16x16x32_bf16 v[56:59], v[146:149], v[186:189], v[56:59]
	v_mfma_f32_16x16x32_bf16 v[48:51], v[162:165], v[186:189], v[48:51]
	v_mfma_f32_16x16x32_bf16 v[40:43], v[146:149], v[194:197], v[40:43]
	v_mfma_f32_16x16x32_bf16 v[32:35], v[162:165], v[194:197], v[32:35]
	v_mfma_f32_16x16x32_bf16 v[24:27], v[146:149], v[202:205], v[24:27]
	v_mfma_f32_16x16x32_bf16 v[16:19], v[162:165], v[202:205], v[16:19]
	v_mfma_f32_16x16x32_bf16 v[8:11], v[146:149], v[210:213], v[8:11]
	v_mfma_f32_16x16x32_bf16 v[0:3], v[162:165], v[210:213], v[0:3]
	v_mfma_f32_16x16x32_bf16 v[56:59], v[158:161], v[190:193], v[56:59]
	v_mfma_f32_16x16x32_bf16 v[48:51], v[166:169], v[190:193], v[48:51]
	v_mfma_f32_16x16x32_bf16 v[40:43], v[158:161], v[198:201], v[40:43]
	v_mfma_f32_16x16x32_bf16 v[32:35], v[166:169], v[198:201], v[32:35]
	v_mfma_f32_16x16x32_bf16 v[24:27], v[158:161], v[206:209], v[24:27]
	v_mfma_f32_16x16x32_bf16 v[16:19], v[166:169], v[206:209], v[16:19]
	v_mfma_f32_16x16x32_bf16 v[8:11], v[158:161], v[214:217], v[8:11]
	v_mfma_f32_16x16x32_bf16 v[0:3], v[166:169], v[214:217], v[0:3]
	v_mfma_f32_16x16x32_bf16 v[60:63], v[170:173], v[186:189], v[60:63]
	v_mfma_f32_16x16x32_bf16 v[52:55], v[178:181], v[186:189], v[52:55]
	v_mfma_f32_16x16x32_bf16 v[44:47], v[170:173], v[194:197], v[44:47]
	v_mfma_f32_16x16x32_bf16 v[36:39], v[178:181], v[194:197], v[36:39]
	v_mfma_f32_16x16x32_bf16 v[28:31], v[170:173], v[202:205], v[28:31]
	v_mfma_f32_16x16x32_bf16 v[20:23], v[178:181], v[202:205], v[20:23]
	v_mfma_f32_16x16x32_bf16 v[12:15], v[170:173], v[210:213], v[12:15]
	v_mfma_f32_16x16x32_bf16 v[4:7], v[178:181], v[210:213], v[4:7]
	v_mfma_f32_16x16x32_bf16 v[60:63], v[174:177], v[190:193], v[60:63]
	v_mfma_f32_16x16x32_bf16 v[52:55], v[182:185], v[190:193], v[52:55]
	v_mfma_f32_16x16x32_bf16 v[44:47], v[174:177], v[198:201], v[44:47]
	v_mfma_f32_16x16x32_bf16 v[36:39], v[182:185], v[198:201], v[36:39]
	v_mfma_f32_16x16x32_bf16 v[28:31], v[174:177], v[206:209], v[28:31]
	v_mfma_f32_16x16x32_bf16 v[20:23], v[182:185], v[206:209], v[20:23]
	v_mfma_f32_16x16x32_bf16 v[12:15], v[174:177], v[214:217], v[12:15]
	v_mfma_f32_16x16x32_bf16 v[4:7], v[182:185], v[214:217], v[4:7]
	s_barrier
	s_add_i32 s23, 0, 0x18000
	s_add_i32 s33, 0, 0x1c000
	v_add_u32_e32 v166, s23, v152
	v_add_u32_e32 v182, s33, v152
	ds_read_b128 v[146:149], v166
	ds_read_b128 v[158:161], v166 offset:1024
	ds_read_b128 v[162:165], v166 offset:2048
	ds_read_b128 v[166:169], v166 offset:3072
	ds_read_b128 v[170:173], v182
	ds_read_b128 v[174:177], v182 offset:1024
	ds_read_b128 v[178:181], v182 offset:2048
	ds_read_b128 v[182:185], v182 offset:3072
	s_add_u32 s44, s44, 0x40000
	s_addc_u32 s45, s45, 0
	s_mov_b32 m0, s54
	v_lshl_add_u64 v[226:227], s[44:45], 0, v[130:131]
	ds_read_b128 v[186:189], v156 offset:32768
	ds_read_b128 v[190:193], v156 offset:33792
	ds_read_b128 v[194:197], v156 offset:34816
	ds_read_b128 v[198:201], v156 offset:35840
	ds_read_b128 v[202:205], v156 offset:36864
	ds_read_b128 v[206:209], v156 offset:37888
	ds_read_b128 v[210:213], v156 offset:38912
	ds_read_b128 v[214:217], v156 offset:39936
	global_load_lds_dwordx4 v[226:227], off
	v_lshl_add_u64 v[226:227], s[44:45], 0, v[134:135]
	s_mov_b32 m0, s55
	s_nop 0
	global_load_lds_dwordx4 v[226:227], off
	s_waitcnt vmcnt(8)
	s_waitcnt lgkmcnt(0)
	s_barrier
	v_mfma_f32_16x16x32_bf16 v[116:119], v[146:149], v[186:189], v[116:119]
	v_mfma_f32_16x16x32_bf16 v[112:115], v[162:165], v[186:189], v[112:115]
	v_mfma_f32_16x16x32_bf16 v[100:103], v[146:149], v[194:197], v[100:103]
	v_mfma_f32_16x16x32_bf16 v[96:99], v[162:165], v[194:197], v[96:99]
	v_mfma_f32_16x16x32_bf16 v[84:87], v[146:149], v[202:205], v[84:87]
	v_mfma_f32_16x16x32_bf16 v[80:83], v[162:165], v[202:205], v[80:83]
	v_mfma_f32_16x16x32_bf16 v[72:75], v[146:149], v[210:213], v[72:75]
	v_mfma_f32_16x16x32_bf16 v[64:67], v[162:165], v[210:213], v[64:67]
	v_mfma_f32_16x16x32_bf16 v[116:119], v[158:161], v[190:193], v[116:119]
	v_mfma_f32_16x16x32_bf16 v[112:115], v[166:169], v[190:193], v[112:115]
	v_mfma_f32_16x16x32_bf16 v[100:103], v[158:161], v[198:201], v[100:103]
	v_mfma_f32_16x16x32_bf16 v[96:99], v[166:169], v[198:201], v[96:99]
	v_mfma_f32_16x16x32_bf16 v[84:87], v[158:161], v[206:209], v[84:87]
	v_mfma_f32_16x16x32_bf16 v[80:83], v[166:169], v[206:209], v[80:83]
	v_mfma_f32_16x16x32_bf16 v[72:75], v[158:161], v[214:217], v[72:75]
	v_mfma_f32_16x16x32_bf16 v[64:67], v[166:169], v[214:217], v[64:67]
	v_mfma_f32_16x16x32_bf16 v[124:127], v[170:173], v[186:189], v[124:127]
	v_mfma_f32_16x16x32_bf16 v[120:123], v[178:181], v[186:189], v[120:123]
	v_mfma_f32_16x16x32_bf16 v[108:111], v[170:173], v[194:197], v[108:111]
	v_mfma_f32_16x16x32_bf16 v[104:107], v[178:181], v[194:197], v[104:107]
	v_mfma_f32_16x16x32_bf16 v[92:95], v[170:173], v[202:205], v[92:95]
	v_mfma_f32_16x16x32_bf16 v[88:91], v[178:181], v[202:205], v[88:91]
	v_mfma_f32_16x16x32_bf16 v[76:79], v[170:173], v[210:213], v[76:79]
	v_mfma_f32_16x16x32_bf16 v[68:71], v[178:181], v[210:213], v[68:71]
	v_mfma_f32_16x16x32_bf16 v[124:127], v[174:177], v[190:193], v[124:127]
	v_mfma_f32_16x16x32_bf16 v[120:123], v[182:185], v[190:193], v[120:123]
	v_mfma_f32_16x16x32_bf16 v[108:111], v[174:177], v[198:201], v[108:111]
	v_mfma_f32_16x16x32_bf16 v[104:107], v[182:185], v[198:201], v[104:107]
	v_mfma_f32_16x16x32_bf16 v[92:95], v[174:177], v[206:209], v[92:95]
	v_mfma_f32_16x16x32_bf16 v[88:91], v[182:185], v[206:209], v[88:91]
	v_mfma_f32_16x16x32_bf16 v[76:79], v[174:177], v[214:217], v[76:79]
	v_mfma_f32_16x16x32_bf16 v[68:71], v[182:185], v[214:217], v[68:71]
	s_barrier
	s_add_i32 s23, s23, s50
	v_lshl_add_u64 v[218:219], v[218:219], 0, s[12:13]
	s_mov_b32 m0, s23
	ds_read_b128 v[186:189], v156 offset:49152
	ds_read_b128 v[190:193], v156 offset:50176
	ds_read_b128 v[194:197], v156 offset:51200
	ds_read_b128 v[198:201], v156 offset:52224
	ds_read_b128 v[202:205], v156 offset:53248
	ds_read_b128 v[206:209], v156 offset:54272
	ds_read_b128 v[210:213], v156 offset:55296
	ds_read_b128 v[214:217], v156 offset:56320
	global_load_lds_dwordx4 v[218:219], off
	s_add_i32 m0, s23, 0x2000
	s_add_u32 s42, s42, 0x40080
	v_lshl_add_u64 v[218:219], v[220:221], 0, s[12:13]
	s_addc_u32 s43, s43, 0
	s_add_i32 s23, s33, s50
	global_load_lds_dwordx4 v[218:219], off
	v_lshl_add_u64 v[218:219], s[42:43], 0, v[132:133]
	s_mov_b32 m0, s23
	s_nop 0
	global_load_lds_dwordx4 v[218:219], off
	v_lshl_add_u64 v[218:219], s[42:43], 0, v[136:137]
	s_add_i32 m0, s23, 0x2000
	s_nop 0
	global_load_lds_dwordx4 v[218:219], off
	v_lshl_add_u64 v[218:219], v[222:223], 0, s[12:13]
	s_mov_b32 m0, s58
	s_nop 0
	global_load_lds_dwordx4 v[218:219], off
	v_lshl_add_u64 v[218:219], v[224:225], 0, s[12:13]
	s_mov_b32 m0, s59
	s_nop 0
	global_load_lds_dwordx4 v[218:219], off
	s_waitcnt vmcnt(8)
	s_waitcnt lgkmcnt(0)
	s_barrier
	v_mfma_f32_16x16x32_bf16 v[56:59], v[146:149], v[186:189], v[56:59]
	v_mfma_f32_16x16x32_bf16 v[48:51], v[162:165], v[186:189], v[48:51]
	v_mfma_f32_16x16x32_bf16 v[40:43], v[146:149], v[194:197], v[40:43]
	v_mfma_f32_16x16x32_bf16 v[32:35], v[162:165], v[194:197], v[32:35]
	v_mfma_f32_16x16x32_bf16 v[24:27], v[146:149], v[202:205], v[24:27]
	v_mfma_f32_16x16x32_bf16 v[16:19], v[162:165], v[202:205], v[16:19]
	v_mfma_f32_16x16x32_bf16 v[8:11], v[146:149], v[210:213], v[8:11]
	v_mfma_f32_16x16x32_bf16 v[0:3], v[162:165], v[210:213], v[0:3]
	v_mfma_f32_16x16x32_bf16 v[56:59], v[158:161], v[190:193], v[56:59]
	v_mfma_f32_16x16x32_bf16 v[48:51], v[166:169], v[190:193], v[48:51]
	v_mfma_f32_16x16x32_bf16 v[40:43], v[158:161], v[198:201], v[40:43]
	v_mfma_f32_16x16x32_bf16 v[32:35], v[166:169], v[198:201], v[32:35]
	v_mfma_f32_16x16x32_bf16 v[24:27], v[158:161], v[206:209], v[24:27]
	v_mfma_f32_16x16x32_bf16 v[16:19], v[166:169], v[206:209], v[16:19]
	v_mfma_f32_16x16x32_bf16 v[8:11], v[158:161], v[214:217], v[8:11]
	v_mfma_f32_16x16x32_bf16 v[0:3], v[166:169], v[214:217], v[0:3]
	v_mfma_f32_16x16x32_bf16 v[60:63], v[170:173], v[186:189], v[60:63]
	v_mfma_f32_16x16x32_bf16 v[52:55], v[178:181], v[186:189], v[52:55]
	v_mfma_f32_16x16x32_bf16 v[44:47], v[170:173], v[194:197], v[44:47]
	v_mfma_f32_16x16x32_bf16 v[36:39], v[178:181], v[194:197], v[36:39]
	v_mfma_f32_16x16x32_bf16 v[28:31], v[170:173], v[202:205], v[28:31]
	v_mfma_f32_16x16x32_bf16 v[20:23], v[178:181], v[202:205], v[20:23]
	v_mfma_f32_16x16x32_bf16 v[12:15], v[170:173], v[210:213], v[12:15]
	v_mfma_f32_16x16x32_bf16 v[4:7], v[178:181], v[210:213], v[4:7]
	v_mfma_f32_16x16x32_bf16 v[60:63], v[174:177], v[190:193], v[60:63]
	v_mfma_f32_16x16x32_bf16 v[52:55], v[182:185], v[190:193], v[52:55]
	v_mfma_f32_16x16x32_bf16 v[44:47], v[174:177], v[198:201], v[44:47]
	v_mfma_f32_16x16x32_bf16 v[36:39], v[182:185], v[198:201], v[36:39]
	v_mfma_f32_16x16x32_bf16 v[28:31], v[174:177], v[206:209], v[28:31]
	v_mfma_f32_16x16x32_bf16 v[20:23], v[182:185], v[206:209], v[20:23]
	v_mfma_f32_16x16x32_bf16 v[12:15], v[174:177], v[214:217], v[12:15]
	v_mfma_f32_16x16x32_bf16 v[4:7], v[182:185], v[214:217], v[4:7]
	s_barrier
	s_add_i32 s67, s67, 2
	s_add_u32 s40, s40, 0x100
	s_addc_u32 s41, s41, 0
	s_add_u32 s65, s65, 0x100
	s_addc_u32 s66, s66, 0
	s_cmp_gt_u32 s67, 13
	s_cbranch_scc0 .LBB0_1342
	s_and_b64 vcc, exec, s[14:15]
	s_cbranch_vccz .LBB0_1345
	s_barrier

.LBB0_1424:
	ds_read_b128 v[146:149], v156
	ds_read_b128 v[160:163], v156 offset:1024
	ds_read_b128 v[164:167], v156 offset:2048
	ds_read_b128 v[168:171], v156 offset:3072
	ds_read_b128 v[172:175], v157
	ds_read_b128 v[176:179], v157 offset:1024
	ds_read_b128 v[180:183], v157 offset:2048
	ds_read_b128 v[184:187], v157 offset:3072
	s_add_u32 s23, s38, 0xfff50080
	s_addc_u32 s33, s39, -1
	s_cmp_eq_u32 s65, 40
	s_cselect_b32 s43, s1, s33
	s_cselect_b32 s42, s0, s23
	s_cselect_b32 s41, s37, s64
	s_cselect_b32 s40, s36, s63
	v_lshl_add_u64 v[220:221], s[38:39], 0, v[138:139]
	s_add_i32 m0, s49, 0xc000
	ds_read_b128 v[188:191], v158
	ds_read_b128 v[192:195], v158 offset:1024
	ds_read_b128 v[196:199], v158 offset:2048
	ds_read_b128 v[200:203], v158 offset:3072
	ds_read_b128 v[204:207], v158 offset:4096
	ds_read_b128 v[208:211], v158 offset:5120
	ds_read_b128 v[212:215], v158 offset:6144
	ds_read_b128 v[216:219], v158 offset:7168
	global_load_lds_dwordx4 v[220:221], off
	v_lshl_add_u64 v[220:221], s[38:39], 0, v[140:141]
	s_add_i32 m0, s49, 0xe000
	s_nop 0
	global_load_lds_dwordx4 v[220:221], off
	s_waitcnt vmcnt(8)
	s_waitcnt lgkmcnt(0)
	s_barrier
	v_mfma_f32_16x16x32_bf16 v[124:127], v[146:149], v[188:191], v[124:127]
	v_mfma_f32_16x16x32_bf16 v[120:123], v[164:167], v[188:191], v[120:123]
	v_mfma_f32_16x16x32_bf16 v[108:111], v[146:149], v[196:199], v[108:111]
	v_mfma_f32_16x16x32_bf16 v[104:107], v[164:167], v[196:199], v[104:107]
	v_mfma_f32_16x16x32_bf16 v[92:95], v[146:149], v[204:207], v[92:95]
	v_mfma_f32_16x16x32_bf16 v[88:91], v[164:167], v[204:207], v[88:91]
	v_mfma_f32_16x16x32_bf16 v[76:79], v[146:149], v[212:215], v[76:79]
	v_mfma_f32_16x16x32_bf16 v[72:75], v[164:167], v[212:215], v[72:75]
	v_mfma_f32_16x16x32_bf16 v[124:127], v[160:163], v[192:195], v[124:127]
	v_mfma_f32_16x16x32_bf16 v[120:123], v[168:171], v[192:195], v[120:123]
	v_mfma_f32_16x16x32_bf16 v[108:111], v[160:163], v[200:203], v[108:111]
	v_mfma_f32_16x16x32_bf16 v[104:107], v[168:171], v[200:203], v[104:107]
	v_mfma_f32_16x16x32_bf16 v[92:95], v[160:163], v[208:211], v[92:95]
	v_mfma_f32_16x16x32_bf16 v[88:91], v[168:171], v[208:211], v[88:91]
	v_mfma_f32_16x16x32_bf16 v[76:79], v[160:163], v[216:219], v[76:79]
	v_mfma_f32_16x16x32_bf16 v[72:75], v[168:171], v[216:219], v[72:75]
	v_mfma_f32_16x16x32_bf16 v[116:119], v[172:175], v[188:191], v[116:119]
	v_mfma_f32_16x16x32_bf16 v[112:115], v[180:183], v[188:191], v[112:115]
	v_mfma_f32_16x16x32_bf16 v[100:103], v[172:175], v[196:199], v[100:103]
	v_mfma_f32_16x16x32_bf16 v[96:99], v[180:183], v[196:199], v[96:99]
	v_mfma_f32_16x16x32_bf16 v[84:87], v[172:175], v[204:207], v[84:87]
	v_mfma_f32_16x16x32_bf16 v[80:83], v[180:183], v[204:207], v[80:83]
	v_mfma_f32_16x16x32_bf16 v[68:71], v[172:175], v[212:215], v[68:71]
	v_mfma_f32_16x16x32_bf16 v[64:67], v[180:183], v[212:215], v[64:67]
	v_mfma_f32_16x16x32_bf16 v[116:119], v[176:179], v[192:195], v[116:119]
	v_mfma_f32_16x16x32_bf16 v[112:115], v[184:187], v[192:195], v[112:115]
	v_mfma_f32_16x16x32_bf16 v[100:103], v[176:179], v[200:203], v[100:103]
	v_mfma_f32_16x16x32_bf16 v[96:99], v[184:187], v[200:203], v[96:99]
	v_mfma_f32_16x16x32_bf16 v[84:87], v[176:179], v[208:211], v[84:87]
	v_mfma_f32_16x16x32_bf16 v[80:83], v[184:187], v[208:211], v[80:83]
	v_mfma_f32_16x16x32_bf16 v[68:71], v[176:179], v[216:219], v[68:71]
	v_mfma_f32_16x16x32_bf16 v[64:67], v[184:187], v[216:219], v[64:67]
	s_barrier
	s_add_i32 s23, s59, s48
	v_lshl_add_u64 v[220:221], s[40:41], 0, v[132:133]
	s_mov_b32 m0, s23
	ds_read_b128 v[188:191], v158 offset:16384
	ds_read_b128 v[192:195], v158 offset:17408
	ds_read_b128 v[196:199], v158 offset:18432
	ds_read_b128 v[200:203], v158 offset:19456
	ds_read_b128 v[204:207], v158 offset:20480
	ds_read_b128 v[208:211], v158 offset:21504
	ds_read_b128 v[212:215], v158 offset:22528
	ds_read_b128 v[216:219], v158 offset:23552
	global_load_lds_dwordx4 v[220:221], off
	s_add_i32 m0, s23, 0x2000
	s_add_u32 s66, s40, 0xb0000
	v_lshl_add_u64 v[222:223], s[40:41], 0, v[136:137]
	s_addc_u32 s67, s41, 0
	s_add_i32 s23, s60, s48
	global_load_lds_dwordx4 v[222:223], off
	v_lshl_add_u64 v[224:225], s[66:67], 0, v[132:133]
	s_mov_b32 m0, s23
	v_lshl_add_u64 v[226:227], s[42:43], 0, v[134:135]
	global_load_lds_dwordx4 v[224:225], off
	v_lshl_add_u64 v[224:225], s[66:67], 0, v[136:137]
	s_add_i32 m0, s23, 0x2000
	s_nop 0
	global_load_lds_dwordx4 v[224:225], off
	v_lshl_add_u64 v[224:225], s[42:43], 0, v[130:131]
	s_mov_b32 m0, s49
	s_nop 0
	global_load_lds_dwordx4 v[224:225], off
	s_mov_b32 m0, s50
	s_nop 0
	global_load_lds_dwordx4 v[226:227], off
	s_waitcnt vmcnt(8)
	s_waitcnt lgkmcnt(0)
	s_barrier
	v_mfma_f32_16x16x32_bf16 v[60:63], v[146:149], v[188:191], v[60:63]
	v_mfma_f32_16x16x32_bf16 v[56:59], v[164:167], v[188:191], v[56:59]
	v_mfma_f32_16x16x32_bf16 v[44:47], v[146:149], v[196:199], v[44:47]
	v_mfma_f32_16x16x32_bf16 v[40:43], v[164:167], v[196:199], v[40:43]
	v_mfma_f32_16x16x32_bf16 v[28:31], v[146:149], v[204:207], v[28:31]
	v_mfma_f32_16x16x32_bf16 v[24:27], v[164:167], v[204:207], v[24:27]
	v_mfma_f32_16x16x32_bf16 v[12:15], v[146:149], v[212:215], v[12:15]
	v_mfma_f32_16x16x32_bf16 v[8:11], v[164:167], v[212:215], v[8:11]
	v_mfma_f32_16x16x32_bf16 v[60:63], v[160:163], v[192:195], v[60:63]
	v_mfma_f32_16x16x32_bf16 v[56:59], v[168:171], v[192:195], v[56:59]
	v_mfma_f32_16x16x32_bf16 v[44:47], v[160:163], v[200:203], v[44:47]
	v_mfma_f32_16x16x32_bf16 v[40:43], v[168:171], v[200:203], v[40:43]
	v_mfma_f32_16x16x32_bf16 v[28:31], v[160:163], v[208:211], v[28:31]
	v_mfma_f32_16x16x32_bf16 v[24:27], v[168:171], v[208:211], v[24:27]
	v_mfma_f32_16x16x32_bf16 v[12:15], v[160:163], v[216:219], v[12:15]
	v_mfma_f32_16x16x32_bf16 v[8:11], v[168:171], v[216:219], v[8:11]
	v_mfma_f32_16x16x32_bf16 v[52:55], v[172:175], v[188:191], v[52:55]
	v_mfma_f32_16x16x32_bf16 v[48:51], v[180:183], v[188:191], v[48:51]
	v_mfma_f32_16x16x32_bf16 v[36:39], v[172:175], v[196:199], v[36:39]
	v_mfma_f32_16x16x32_bf16 v[32:35], v[180:183], v[196:199], v[32:35]
	v_mfma_f32_16x16x32_bf16 v[20:23], v[172:175], v[204:207], v[20:23]
	v_mfma_f32_16x16x32_bf16 v[16:19], v[180:183], v[204:207], v[16:19]
	v_mfma_f32_16x16x32_bf16 v[4:7], v[172:175], v[212:215], v[4:7]
	v_mfma_f32_16x16x32_bf16 v[0:3], v[180:183], v[212:215], v[0:3]
	v_mfma_f32_16x16x32_bf16 v[52:55], v[176:179], v[192:195], v[52:55]
	v_mfma_f32_16x16x32_bf16 v[48:51], v[184:187], v[192:195], v[48:51]
	v_mfma_f32_16x16x32_bf16 v[36:39], v[176:179], v[200:203], v[36:39]
	v_mfma_f32_16x16x32_bf16 v[32:35], v[184:187], v[200:203], v[32:35]
	v_mfma_f32_16x16x32_bf16 v[20:23], v[176:179], v[208:211], v[20:23]
	v_mfma_f32_16x16x32_bf16 v[16:19], v[184:187], v[208:211], v[16:19]
	v_mfma_f32_16x16x32_bf16 v[4:7], v[176:179], v[216:219], v[4:7]
	v_mfma_f32_16x16x32_bf16 v[0:3], v[184:187], v[216:219], v[0:3]
	s_barrier
	s_add_i32 s23, 0, 0x18000
	s_add_i32 s33, 0, 0x1c000
	v_add_u32_e32 v168, s23, v154
	v_add_u32_e32 v184, s33, v154
	ds_read_b128 v[146:149], v168
	ds_read_b128 v[160:163], v168 offset:1024
	ds_read_b128 v[164:167], v168 offset:2048
	ds_read_b128 v[168:171], v168 offset:3072
	ds_read_b128 v[172:175], v184
	ds_read_b128 v[176:179], v184 offset:1024
	ds_read_b128 v[180:183], v184 offset:2048
	ds_read_b128 v[184:187], v184 offset:3072
	s_add_u32 s42, s42, 0xb0000
	s_addc_u32 s43, s43, 0
	s_mov_b32 m0, s51
	v_lshl_add_u64 v[228:229], s[42:43], 0, v[130:131]
	ds_read_b128 v[188:191], v158 offset:32768
	ds_read_b128 v[192:195], v158 offset:33792
	ds_read_b128 v[196:199], v158 offset:34816
	ds_read_b128 v[200:203], v158 offset:35840
	ds_read_b128 v[204:207], v158 offset:36864
	ds_read_b128 v[208:211], v158 offset:37888
	ds_read_b128 v[212:215], v158 offset:38912
	ds_read_b128 v[216:219], v158 offset:39936
	global_load_lds_dwordx4 v[228:229], off
	v_lshl_add_u64 v[228:229], s[42:43], 0, v[134:135]
	s_mov_b32 m0, s52
	s_nop 0
	global_load_lds_dwordx4 v[228:229], off
	s_waitcnt vmcnt(8)
	s_waitcnt lgkmcnt(0)
	s_barrier
	v_mfma_f32_16x16x32_bf16 v[124:127], v[146:149], v[188:191], v[124:127]
	v_mfma_f32_16x16x32_bf16 v[120:123], v[164:167], v[188:191], v[120:123]
	v_mfma_f32_16x16x32_bf16 v[108:111], v[146:149], v[196:199], v[108:111]
	v_mfma_f32_16x16x32_bf16 v[104:107], v[164:167], v[196:199], v[104:107]
	v_mfma_f32_16x16x32_bf16 v[92:95], v[146:149], v[204:207], v[92:95]
	v_mfma_f32_16x16x32_bf16 v[88:91], v[164:167], v[204:207], v[88:91]
	v_mfma_f32_16x16x32_bf16 v[76:79], v[146:149], v[212:215], v[76:79]
	v_mfma_f32_16x16x32_bf16 v[72:75], v[164:167], v[212:215], v[72:75]
	v_mfma_f32_16x16x32_bf16 v[124:127], v[160:163], v[192:195], v[124:127]
	v_mfma_f32_16x16x32_bf16 v[120:123], v[168:171], v[192:195], v[120:123]
	v_mfma_f32_16x16x32_bf16 v[108:111], v[160:163], v[200:203], v[108:111]
	v_mfma_f32_16x16x32_bf16 v[104:107], v[168:171], v[200:203], v[104:107]
	v_mfma_f32_16x16x32_bf16 v[92:95], v[160:163], v[208:211], v[92:95]
	v_mfma_f32_16x16x32_bf16 v[88:91], v[168:171], v[208:211], v[88:91]
	v_mfma_f32_16x16x32_bf16 v[76:79], v[160:163], v[216:219], v[76:79]
	v_mfma_f32_16x16x32_bf16 v[72:75], v[168:171], v[216:219], v[72:75]
	v_mfma_f32_16x16x32_bf16 v[116:119], v[172:175], v[188:191], v[116:119]
	v_mfma_f32_16x16x32_bf16 v[112:115], v[180:183], v[188:191], v[112:115]
	v_mfma_f32_16x16x32_bf16 v[100:103], v[172:175], v[196:199], v[100:103]
	v_mfma_f32_16x16x32_bf16 v[96:99], v[180:183], v[196:199], v[96:99]
	v_mfma_f32_16x16x32_bf16 v[84:87], v[172:175], v[204:207], v[84:87]
	v_mfma_f32_16x16x32_bf16 v[80:83], v[180:183], v[204:207], v[80:83]
	v_mfma_f32_16x16x32_bf16 v[68:71], v[172:175], v[212:215], v[68:71]
	v_mfma_f32_16x16x32_bf16 v[64:67], v[180:183], v[212:215], v[64:67]
	v_mfma_f32_16x16x32_bf16 v[116:119], v[176:179], v[192:195], v[116:119]
	v_mfma_f32_16x16x32_bf16 v[112:115], v[184:187], v[192:195], v[112:115]
	v_mfma_f32_16x16x32_bf16 v[100:103], v[176:179], v[200:203], v[100:103]
	v_mfma_f32_16x16x32_bf16 v[96:99], v[184:187], v[200:203], v[96:99]
	v_mfma_f32_16x16x32_bf16 v[84:87], v[176:179], v[208:211], v[84:87]
	v_mfma_f32_16x16x32_bf16 v[80:83], v[184:187], v[208:211], v[80:83]
	v_mfma_f32_16x16x32_bf16 v[68:71], v[176:179], v[216:219], v[68:71]
	v_mfma_f32_16x16x32_bf16 v[64:67], v[184:187], v[216:219], v[64:67]
	s_barrier
	s_add_i32 s23, s23, s48
	v_lshl_add_u64 v[220:221], v[220:221], 0, s[16:17]
	s_mov_b32 m0, s23
	ds_read_b128 v[188:191], v158 offset:49152
	ds_read_b128 v[192:195], v158 offset:50176
	ds_read_b128 v[196:199], v158 offset:51200
	ds_read_b128 v[200:203], v158 offset:52224
	ds_read_b128 v[204:207], v158 offset:53248
	ds_read_b128 v[208:211], v158 offset:54272
	ds_read_b128 v[212:215], v158 offset:55296
	ds_read_b128 v[216:219], v158 offset:56320
	global_load_lds_dwordx4 v[220:221], off
	s_add_i32 m0, s23, 0x2000
	s_add_u32 s40, s40, 0xb0080
	v_lshl_add_u64 v[220:221], v[222:223], 0, s[16:17]
	s_addc_u32 s41, s41, 0
	s_add_i32 s23, s33, s48
	global_load_lds_dwordx4 v[220:221], off
	v_lshl_add_u64 v[220:221], s[40:41], 0, v[132:133]
	s_mov_b32 m0, s23
	s_nop 0
	global_load_lds_dwordx4 v[220:221], off
	v_lshl_add_u64 v[220:221], s[40:41], 0, v[136:137]
	s_add_i32 m0, s23, 0x2000
	s_nop 0
	global_load_lds_dwordx4 v[220:221], off
	v_lshl_add_u64 v[220:221], v[224:225], 0, s[16:17]
	s_mov_b32 m0, s56
	s_nop 0
	global_load_lds_dwordx4 v[220:221], off
	v_lshl_add_u64 v[220:221], v[226:227], 0, s[16:17]
	s_mov_b32 m0, s57
	s_nop 0
	global_load_lds_dwordx4 v[220:221], off
	s_waitcnt vmcnt(8)
	s_waitcnt lgkmcnt(0)
	s_barrier
	v_mfma_f32_16x16x32_bf16 v[60:63], v[146:149], v[188:191], v[60:63]
	v_mfma_f32_16x16x32_bf16 v[56:59], v[164:167], v[188:191], v[56:59]
	v_mfma_f32_16x16x32_bf16 v[44:47], v[146:149], v[196:199], v[44:47]
	v_mfma_f32_16x16x32_bf16 v[40:43], v[164:167], v[196:199], v[40:43]
	v_mfma_f32_16x16x32_bf16 v[28:31], v[146:149], v[204:207], v[28:31]
	v_mfma_f32_16x16x32_bf16 v[24:27], v[164:167], v[204:207], v[24:27]
	v_mfma_f32_16x16x32_bf16 v[12:15], v[146:149], v[212:215], v[12:15]
	v_mfma_f32_16x16x32_bf16 v[8:11], v[164:167], v[212:215], v[8:11]
	v_mfma_f32_16x16x32_bf16 v[60:63], v[160:163], v[192:195], v[60:63]
	v_mfma_f32_16x16x32_bf16 v[56:59], v[168:171], v[192:195], v[56:59]
	v_mfma_f32_16x16x32_bf16 v[44:47], v[160:163], v[200:203], v[44:47]
	v_mfma_f32_16x16x32_bf16 v[40:43], v[168:171], v[200:203], v[40:43]
	v_mfma_f32_16x16x32_bf16 v[28:31], v[160:163], v[208:211], v[28:31]
	v_mfma_f32_16x16x32_bf16 v[24:27], v[168:171], v[208:211], v[24:27]
	v_mfma_f32_16x16x32_bf16 v[12:15], v[160:163], v[216:219], v[12:15]
	v_mfma_f32_16x16x32_bf16 v[8:11], v[168:171], v[216:219], v[8:11]
	v_mfma_f32_16x16x32_bf16 v[52:55], v[172:175], v[188:191], v[52:55]
	v_mfma_f32_16x16x32_bf16 v[48:51], v[180:183], v[188:191], v[48:51]
	v_mfma_f32_16x16x32_bf16 v[36:39], v[172:175], v[196:199], v[36:39]
	v_mfma_f32_16x16x32_bf16 v[32:35], v[180:183], v[196:199], v[32:35]
	v_mfma_f32_16x16x32_bf16 v[20:23], v[172:175], v[204:207], v[20:23]
	v_mfma_f32_16x16x32_bf16 v[16:19], v[180:183], v[204:207], v[16:19]
	v_mfma_f32_16x16x32_bf16 v[4:7], v[172:175], v[212:215], v[4:7]
	v_mfma_f32_16x16x32_bf16 v[0:3], v[180:183], v[212:215], v[0:3]
	v_mfma_f32_16x16x32_bf16 v[52:55], v[176:179], v[192:195], v[52:55]
	v_mfma_f32_16x16x32_bf16 v[48:51], v[184:187], v[192:195], v[48:51]
	v_mfma_f32_16x16x32_bf16 v[36:39], v[176:179], v[200:203], v[36:39]
	v_mfma_f32_16x16x32_bf16 v[32:35], v[184:187], v[200:203], v[32:35]
	v_mfma_f32_16x16x32_bf16 v[20:23], v[176:179], v[208:211], v[20:23]
	v_mfma_f32_16x16x32_bf16 v[16:19], v[184:187], v[208:211], v[16:19]
	v_mfma_f32_16x16x32_bf16 v[4:7], v[176:179], v[216:219], v[4:7]
	v_mfma_f32_16x16x32_bf16 v[0:3], v[184:187], v[216:219], v[0:3]
	s_barrier
	s_add_i32 s65, s65, 2
	s_add_u32 s38, s38, 0x100
	s_addc_u32 s39, s39, 0
	s_add_u32 s63, s63, 0x100
	s_addc_u32 s64, s64, 0
	s_cmp_gt_u32 s65, 41
	s_cbranch_scc0 .LBB0_1424
	s_and_b64 vcc, exec, s[18:19]
	s_cbranch_vccz .LBB0_1427
	s_barrier
